# static prio 1 for waves 4-7 (flips deleted) + s_nop 0 between same-accumulator int8 MFMAs removed
# speedup vs baseline: 1.0077x; 1.0077x over previous
.LBB0_308:
	ds_read_b128 v[142:145], v191
	ds_read_b128 v[138:141], v191 offset:1024
	ds_read_b128 v[134:137], v191 offset:2048
	ds_read_b128 v[130:133], v191 offset:3072
	s_add_u32 s46, s44, 0xfff80080
	s_addc_u32 s47, s45, -1
	s_cmp_eq_u32 s37, 28
	s_cselect_b32 s49, s0, s47
	s_cselect_b32 s48, s1, s46
	s_cselect_b32 s47, s7, s31
	s_cselect_b32 s46, s14, s15
	v_lshl_add_u64 v[166:167], s[44:45], 0, v[162:163]
	s_add_i32 m0, s9, 0xc000
	ds_read_b128 v[170:173], v192
	ds_read_b128 v[174:177], v192 offset:1024
	s_waitcnt lgkmcnt(0)
	ds_read_b128 v[178:181], v192 offset:2048
	ds_read_b128 v[182:185], v192 offset:3072
	ds_read_b128 v[204:207], v192 offset:4096
	ds_read_b128 v[208:211], v192 offset:5120
	ds_read_b128 v[212:215], v192 offset:6144
	ds_read_b128 v[216:219], v192 offset:7168
	global_load_lds_dwordx4 v[166:167], off
	v_lshl_add_u64 v[166:167], s[44:45], 0, v[164:165]
	s_add_i32 m0, s9, 0xe000
	s_nop 0
	global_load_lds_dwordx4 v[166:167], off
	s_waitcnt lgkmcnt(8)
	s_barrier
	s_waitcnt lgkmcnt(0)
	s_waitcnt lgkmcnt(0)
	v_mfma_i32_16x16x64_i8 v[126:129], v[142:145], v[170:173], v[126:129]
	v_mfma_i32_16x16x64_i8 v[126:129], v[138:141], v[174:177], v[126:129]
	v_mfma_i32_16x16x64_i8 v[122:125], v[134:137], v[170:173], v[122:125]
	v_mfma_i32_16x16x64_i8 v[122:125], v[130:133], v[174:177], v[122:125]
	v_mfma_i32_16x16x64_i8 v[110:113], v[142:145], v[178:181], v[110:113]
	v_mfma_i32_16x16x64_i8 v[110:113], v[138:141], v[182:185], v[110:113]
	v_mfma_i32_16x16x64_i8 v[106:109], v[134:137], v[178:181], v[106:109]
	v_mfma_i32_16x16x64_i8 v[106:109], v[130:133], v[182:185], v[106:109]
	v_mfma_i32_16x16x64_i8 v[94:97], v[142:145], v[204:207], v[94:97]
	v_mfma_i32_16x16x64_i8 v[94:97], v[138:141], v[208:211], v[94:97]
	v_mfma_i32_16x16x64_i8 v[90:93], v[134:137], v[204:207], v[90:93]
	v_mfma_i32_16x16x64_i8 v[90:93], v[130:133], v[208:211], v[90:93]
	v_mfma_i32_16x16x64_i8 v[78:81], v[142:145], v[212:215], v[78:81]
	v_mfma_i32_16x16x64_i8 v[78:81], v[138:141], v[216:219], v[78:81]
	v_mfma_i32_16x16x64_i8 v[74:77], v[134:137], v[212:215], v[74:77]
	v_mfma_i32_16x16x64_i8 v[74:77], v[130:133], v[216:219], v[74:77]
	s_barrier
	s_add_i32 s50, s55, s8
	v_lshl_add_u64 v[166:167], s[46:47], 0, v[148:149]
	s_mov_b32 m0, s50
	ds_read_b128 v[220:223], v193
	ds_read_b128 v[224:227], v193 offset:1024
	ds_read_b128 v[234:237], v193 offset:2048
	ds_read_b128 v[238:241], v193 offset:3072
	global_load_lds_dwordx4 v[166:167], off
	v_lshl_add_u64 v[168:169], s[46:47], 0, v[152:153]
	s_add_i32 m0, s50, 0x2000
	s_nop 0
	global_load_lds_dwordx4 v[168:169], off
	s_barrier
	s_waitcnt lgkmcnt(0)
	s_waitcnt lgkmcnt(0)
	v_mfma_i32_16x16x64_i8 v[118:121], v[220:223], v[170:173], v[118:121]
	v_mfma_i32_16x16x64_i8 v[118:121], v[224:227], v[174:177], v[118:121]
	v_mfma_i32_16x16x64_i8 v[114:117], v[234:237], v[170:173], v[114:117]
	v_mfma_i32_16x16x64_i8 v[114:117], v[238:241], v[174:177], v[114:117]
	v_mfma_i32_16x16x64_i8 v[102:105], v[220:223], v[178:181], v[102:105]
	v_mfma_i32_16x16x64_i8 v[102:105], v[224:227], v[182:185], v[102:105]
	v_mfma_i32_16x16x64_i8 v[98:101], v[234:237], v[178:181], v[98:101]
	v_mfma_i32_16x16x64_i8 v[98:101], v[238:241], v[182:185], v[98:101]
	v_mfma_i32_16x16x64_i8 v[86:89], v[220:223], v[204:207], v[86:89]
	v_mfma_i32_16x16x64_i8 v[86:89], v[224:227], v[208:211], v[86:89]
	v_mfma_i32_16x16x64_i8 v[82:85], v[234:237], v[204:207], v[82:85]
	v_mfma_i32_16x16x64_i8 v[82:85], v[238:241], v[208:211], v[82:85]
	v_mfma_i32_16x16x64_i8 v[70:73], v[220:223], v[212:215], v[70:73]
	v_mfma_i32_16x16x64_i8 v[70:73], v[224:227], v[216:219], v[70:73]
	v_mfma_i32_16x16x64_i8 v[66:69], v[234:237], v[212:215], v[66:69]
	v_mfma_i32_16x16x64_i8 v[66:69], v[238:241], v[216:219], v[66:69]
	s_mov_b32 m0, s9
	v_lshl_add_u64 v[170:171], s[48:49], 0, v[146:147]
	s_barrier
	ds_read_b128 v[174:177], v192 offset:16384
	ds_read_b128 v[178:181], v192 offset:17408
	ds_read_b128 v[182:185], v192 offset:18432
	ds_read_b128 v[204:207], v192 offset:19456
	ds_read_b128 v[208:211], v192 offset:20480
	ds_read_b128 v[212:215], v192 offset:21504
	ds_read_b128 v[216:219], v192 offset:22528
	ds_read_b128 v[242:245], v192 offset:23552
	global_load_lds_dwordx4 v[170:171], off
	v_lshl_add_u64 v[172:173], s[48:49], 0, v[150:151]
	s_mov_b32 m0, s13
	s_nop 0
	global_load_lds_dwordx4 v[172:173], off
	s_barrier
	s_waitcnt lgkmcnt(0)
	s_waitcnt lgkmcnt(0)
	v_mfma_i32_16x16x64_i8 v[62:65], v[142:145], v[174:177], v[62:65]
	v_mfma_i32_16x16x64_i8 v[62:65], v[138:141], v[178:181], v[62:65]
	v_mfma_i32_16x16x64_i8 v[58:61], v[134:137], v[174:177], v[58:61]
	v_mfma_i32_16x16x64_i8 v[58:61], v[130:133], v[178:181], v[58:61]
	v_mfma_i32_16x16x64_i8 v[46:49], v[142:145], v[182:185], v[46:49]
	v_mfma_i32_16x16x64_i8 v[46:49], v[138:141], v[204:207], v[46:49]
	v_mfma_i32_16x16x64_i8 v[42:45], v[134:137], v[182:185], v[42:45]
	v_mfma_i32_16x16x64_i8 v[42:45], v[130:133], v[204:207], v[42:45]
	v_mfma_i32_16x16x64_i8 v[30:33], v[142:145], v[208:211], v[30:33]
	v_mfma_i32_16x16x64_i8 v[30:33], v[138:141], v[212:215], v[30:33]
	v_mfma_i32_16x16x64_i8 v[26:29], v[134:137], v[208:211], v[26:29]
	v_mfma_i32_16x16x64_i8 v[26:29], v[130:133], v[212:215], v[26:29]
	v_mfma_i32_16x16x64_i8 v[14:17], v[142:145], v[216:219], v[14:17]
	v_mfma_i32_16x16x64_i8 v[14:17], v[138:141], v[242:245], v[14:17]
	v_mfma_i32_16x16x64_i8 v[10:13], v[134:137], v[216:219], v[10:13]
	v_mfma_i32_16x16x64_i8 v[10:13], v[130:133], v[242:245], v[10:13]
	s_barrier
	s_add_u32 s50, s46, 0x80000
	s_addc_u32 s51, s47, 0
	s_add_i32 s59, s56, s8
	v_lshl_add_u64 v[130:131], s[50:51], 0, v[148:149]
	s_mov_b32 m0, s59
	s_nop 0
	global_load_lds_dwordx4 v[130:131], off
	v_lshl_add_u64 v[130:131], s[50:51], 0, v[152:153]
	s_add_i32 m0, s59, 0x2000
	s_nop 0
	global_load_lds_dwordx4 v[130:131], off
	s_waitcnt vmcnt(6)
	s_barrier
	v_mfma_i32_16x16x64_i8 v[54:57], v[220:223], v[174:177], v[54:57]
	v_mfma_i32_16x16x64_i8 v[54:57], v[224:227], v[178:181], v[54:57]
	v_mfma_i32_16x16x64_i8 v[50:53], v[234:237], v[174:177], v[50:53]
	v_mfma_i32_16x16x64_i8 v[50:53], v[238:241], v[178:181], v[50:53]
	v_mfma_i32_16x16x64_i8 v[38:41], v[220:223], v[182:185], v[38:41]
	v_mfma_i32_16x16x64_i8 v[38:41], v[224:227], v[204:207], v[38:41]
	v_mfma_i32_16x16x64_i8 v[34:37], v[234:237], v[182:185], v[34:37]
	v_mfma_i32_16x16x64_i8 v[34:37], v[238:241], v[204:207], v[34:37]
	v_mfma_i32_16x16x64_i8 v[22:25], v[220:223], v[208:211], v[22:25]
	v_mfma_i32_16x16x64_i8 v[22:25], v[224:227], v[212:215], v[22:25]
	v_mfma_i32_16x16x64_i8 v[18:21], v[234:237], v[208:211], v[18:21]
	v_mfma_i32_16x16x64_i8 v[18:21], v[238:241], v[212:215], v[18:21]
	v_mfma_i32_16x16x64_i8 v[6:9], v[220:223], v[216:219], v[6:9]
	v_mfma_i32_16x16x64_i8 v[6:9], v[224:227], v[242:245], v[6:9]
	v_mfma_i32_16x16x64_i8 v[2:5], v[234:237], v[216:219], v[2:5]
	v_mfma_i32_16x16x64_i8 v[2:5], v[238:241], v[242:245], v[2:5]
	s_add_i32 s50, 0, 0x18000
	v_add_u32_e32 v142, s50, v188
	s_barrier
	ds_read_b128 v[130:133], v142
	ds_read_b128 v[134:137], v142 offset:1024
	ds_read_b128 v[138:141], v142 offset:2048
	ds_read_b128 v[142:145], v142 offset:3072
	s_add_u32 s48, s48, 0x80000
	s_addc_u32 s49, s49, 0
	s_mov_b32 m0, s29
	v_lshl_add_u64 v[186:187], s[48:49], 0, v[146:147]
	ds_read_b128 v[174:177], v192 offset:32768
	ds_read_b128 v[178:181], v192 offset:33792
	ds_read_b128 v[182:185], v192 offset:34816
	ds_read_b128 v[204:207], v192 offset:35840
	ds_read_b128 v[208:211], v192 offset:36864
	ds_read_b128 v[212:215], v192 offset:37888
	ds_read_b128 v[216:219], v192 offset:38912
	ds_read_b128 v[220:223], v192 offset:39936
	global_load_lds_dwordx4 v[186:187], off
	v_lshl_add_u64 v[186:187], s[48:49], 0, v[150:151]
	s_mov_b32 m0, s33
	s_nop 0
	global_load_lds_dwordx4 v[186:187], off
	s_waitcnt lgkmcnt(8)
	s_barrier
	s_waitcnt lgkmcnt(0)
	s_waitcnt lgkmcnt(0)
	v_mfma_i32_16x16x64_i8 v[126:129], v[130:133], v[174:177], v[126:129]
	v_mfma_i32_16x16x64_i8 v[126:129], v[134:137], v[178:181], v[126:129]
	v_mfma_i32_16x16x64_i8 v[122:125], v[138:141], v[174:177], v[122:125]
	v_mfma_i32_16x16x64_i8 v[122:125], v[142:145], v[178:181], v[122:125]
	v_mfma_i32_16x16x64_i8 v[110:113], v[130:133], v[182:185], v[110:113]
	v_mfma_i32_16x16x64_i8 v[110:113], v[134:137], v[204:207], v[110:113]
	v_mfma_i32_16x16x64_i8 v[106:109], v[138:141], v[182:185], v[106:109]
	v_mfma_i32_16x16x64_i8 v[106:109], v[142:145], v[204:207], v[106:109]
	v_mfma_i32_16x16x64_i8 v[94:97], v[130:133], v[208:211], v[94:97]
	v_mfma_i32_16x16x64_i8 v[94:97], v[134:137], v[212:215], v[94:97]
	v_mfma_i32_16x16x64_i8 v[90:93], v[138:141], v[208:211], v[90:93]
	v_mfma_i32_16x16x64_i8 v[90:93], v[142:145], v[212:215], v[90:93]
	v_mfma_i32_16x16x64_i8 v[78:81], v[130:133], v[216:219], v[78:81]
	v_mfma_i32_16x16x64_i8 v[78:81], v[134:137], v[220:223], v[78:81]
	v_mfma_i32_16x16x64_i8 v[74:77], v[138:141], v[216:219], v[74:77]
	v_mfma_i32_16x16x64_i8 v[74:77], v[142:145], v[220:223], v[74:77]
	s_barrier
	s_add_i32 s48, 0, 0x1c000
	s_add_i32 s49, s50, s8
	v_add_u32_e32 v156, s48, v188
	v_lshl_add_u64 v[166:167], v[166:167], 0, s[22:23]
	s_mov_b32 m0, s49
	ds_read_b128 v[224:227], v156
	ds_read_b128 v[234:237], v156 offset:1024
	ds_read_b128 v[238:241], v156 offset:2048
	ds_read_b128 v[242:245], v156 offset:3072
	global_load_lds_dwordx4 v[166:167], off
	v_lshl_add_u64 v[166:167], v[168:169], 0, s[22:23]
	s_add_i32 m0, s49, 0x2000
	s_nop 0
	global_load_lds_dwordx4 v[166:167], off
	s_barrier
	s_waitcnt lgkmcnt(0)
	s_waitcnt lgkmcnt(0)
	v_mfma_i32_16x16x64_i8 v[118:121], v[224:227], v[174:177], v[118:121]
	v_mfma_i32_16x16x64_i8 v[118:121], v[234:237], v[178:181], v[118:121]
	v_mfma_i32_16x16x64_i8 v[114:117], v[238:241], v[174:177], v[114:117]
	v_mfma_i32_16x16x64_i8 v[114:117], v[242:245], v[178:181], v[114:117]
	v_mfma_i32_16x16x64_i8 v[102:105], v[224:227], v[182:185], v[102:105]
	v_mfma_i32_16x16x64_i8 v[102:105], v[234:237], v[204:207], v[102:105]
	v_mfma_i32_16x16x64_i8 v[98:101], v[238:241], v[182:185], v[98:101]
	v_mfma_i32_16x16x64_i8 v[98:101], v[242:245], v[204:207], v[98:101]
	v_mfma_i32_16x16x64_i8 v[86:89], v[224:227], v[208:211], v[86:89]
	v_mfma_i32_16x16x64_i8 v[86:89], v[234:237], v[212:215], v[86:89]
	v_mfma_i32_16x16x64_i8 v[82:85], v[238:241], v[208:211], v[82:85]
	v_mfma_i32_16x16x64_i8 v[82:85], v[242:245], v[212:215], v[82:85]
	v_mfma_i32_16x16x64_i8 v[70:73], v[224:227], v[216:219], v[70:73]
	v_mfma_i32_16x16x64_i8 v[70:73], v[234:237], v[220:223], v[70:73]
	v_mfma_i32_16x16x64_i8 v[66:69], v[238:241], v[216:219], v[66:69]
	v_mfma_i32_16x16x64_i8 v[66:69], v[242:245], v[220:223], v[66:69]
	s_mov_b32 m0, s53
	v_lshl_add_u64 v[170:171], v[170:171], 0, s[22:23]
	s_barrier
	ds_read_b128 v[166:169], v192 offset:49152
	ds_read_b128 v[174:177], v192 offset:50176
	ds_read_b128 v[178:181], v192 offset:51200
	ds_read_b128 v[182:185], v192 offset:52224
	ds_read_b128 v[204:207], v192 offset:53248
	ds_read_b128 v[208:211], v192 offset:54272
	ds_read_b128 v[212:215], v192 offset:55296
	ds_read_b128 v[216:219], v192 offset:56320
	global_load_lds_dwordx4 v[170:171], off
	v_lshl_add_u64 v[170:171], v[172:173], 0, s[22:23]
	s_mov_b32 m0, s54
	s_nop 0
	global_load_lds_dwordx4 v[170:171], off
	s_barrier
	s_waitcnt lgkmcnt(0)
	s_waitcnt lgkmcnt(0)
	v_mfma_i32_16x16x64_i8 v[62:65], v[130:133], v[166:169], v[62:65]
	v_mfma_i32_16x16x64_i8 v[62:65], v[134:137], v[174:177], v[62:65]
	v_mfma_i32_16x16x64_i8 v[58:61], v[138:141], v[166:169], v[58:61]
	v_mfma_i32_16x16x64_i8 v[58:61], v[142:145], v[174:177], v[58:61]
	v_mfma_i32_16x16x64_i8 v[46:49], v[130:133], v[178:181], v[46:49]
	v_mfma_i32_16x16x64_i8 v[46:49], v[134:137], v[182:185], v[46:49]
	v_mfma_i32_16x16x64_i8 v[42:45], v[138:141], v[178:181], v[42:45]
	v_mfma_i32_16x16x64_i8 v[42:45], v[142:145], v[182:185], v[42:45]
	v_mfma_i32_16x16x64_i8 v[30:33], v[130:133], v[204:207], v[30:33]
	v_mfma_i32_16x16x64_i8 v[30:33], v[134:137], v[208:211], v[30:33]
	v_mfma_i32_16x16x64_i8 v[26:29], v[138:141], v[204:207], v[26:29]
	v_mfma_i32_16x16x64_i8 v[26:29], v[142:145], v[208:211], v[26:29]
	v_mfma_i32_16x16x64_i8 v[14:17], v[130:133], v[212:215], v[14:17]
	v_mfma_i32_16x16x64_i8 v[14:17], v[134:137], v[216:219], v[14:17]
	v_mfma_i32_16x16x64_i8 v[10:13], v[138:141], v[212:215], v[10:13]
	v_mfma_i32_16x16x64_i8 v[10:13], v[142:145], v[216:219], v[10:13]
	s_barrier
	s_add_u32 s46, s46, 0x80080
	s_addc_u32 s47, s47, 0
	s_add_i32 s48, s48, s8
	v_lshl_add_u64 v[130:131], s[46:47], 0, v[148:149]
	s_mov_b32 m0, s48
	s_nop 0
	global_load_lds_dwordx4 v[130:131], off
	v_lshl_add_u64 v[130:131], s[46:47], 0, v[152:153]
	s_add_i32 m0, s48, 0x2000
	s_nop 0
	global_load_lds_dwordx4 v[130:131], off
	s_waitcnt vmcnt(6)
	s_barrier
	v_mfma_i32_16x16x64_i8 v[54:57], v[224:227], v[166:169], v[54:57]
	v_mfma_i32_16x16x64_i8 v[54:57], v[234:237], v[174:177], v[54:57]
	v_mfma_i32_16x16x64_i8 v[50:53], v[238:241], v[166:169], v[50:53]
	v_mfma_i32_16x16x64_i8 v[50:53], v[242:245], v[174:177], v[50:53]
	v_mfma_i32_16x16x64_i8 v[38:41], v[224:227], v[178:181], v[38:41]
	v_mfma_i32_16x16x64_i8 v[38:41], v[234:237], v[182:185], v[38:41]
	v_mfma_i32_16x16x64_i8 v[34:37], v[238:241], v[178:181], v[34:37]
	v_mfma_i32_16x16x64_i8 v[34:37], v[242:245], v[182:185], v[34:37]
	v_mfma_i32_16x16x64_i8 v[22:25], v[224:227], v[204:207], v[22:25]
	v_mfma_i32_16x16x64_i8 v[22:25], v[234:237], v[208:211], v[22:25]
	v_mfma_i32_16x16x64_i8 v[18:21], v[238:241], v[204:207], v[18:21]
	v_mfma_i32_16x16x64_i8 v[18:21], v[242:245], v[208:211], v[18:21]
	v_mfma_i32_16x16x64_i8 v[6:9], v[224:227], v[212:215], v[6:9]
	v_mfma_i32_16x16x64_i8 v[6:9], v[234:237], v[216:219], v[6:9]
	v_mfma_i32_16x16x64_i8 v[2:5], v[238:241], v[212:215], v[2:5]
	v_mfma_i32_16x16x64_i8 v[2:5], v[242:245], v[216:219], v[2:5]
	s_add_i32 s37, s37, 2
	s_add_u32 s44, s44, 0x100
	s_addc_u32 s45, s45, 0
	s_add_u32 s15, s15, 0x100
	s_addc_u32 s31, s31, 0
	s_cmp_gt_u32 s37, 29
	s_barrier
	s_cbranch_scc0 .LBB0_308
	s_nop 15
	s_nop 15
	s_and_b64 vcc, exec, s[24:25]
	s_cbranch_vccz .LBB0_311
	s_barrier

.LBB0_734:
	ds_read_b128 v[158:161], v227
	ds_read_b128 v[154:157], v227 offset:1024
	ds_read_b128 v[150:153], v227 offset:2048
	ds_read_b128 v[146:149], v227 offset:3072
	ds_read_b128 v[62:65], v233
	ds_read_b128 v[58:61], v233 offset:1024
	ds_read_b128 v[54:57], v233 offset:2048
	ds_read_b128 v[50:53], v233 offset:3072
	s_add_u32 s14, s30, s34
	s_addc_u32 s15, s31, s35
	s_add_u32 s14, s14, 0x100
	s_addc_u32 s15, s15, 0
	s_add_u32 s25, s77, s34
	s_addc_u32 s29, s78, s35
	s_cmpk_eq_i32 s34, 0xf00
	s_cselect_b32 s41, s31, s15
	s_cselect_b32 s40, s30, s14
	s_cselect_b32 s39, s1, s29
	s_cselect_b32 s38, s0, s25
	s_add_i32 s66, s23, 0xc000
	v_lshl_add_u64 v[240:241], v[162:163], 0, s[34:35]
	s_mov_b32 m0, s66
	s_add_i32 s67, s23, 0xe000
	ds_read_b128 v[166:169], v226
	ds_read_b128 v[170:173], v226 offset:1024
	ds_read_b128 v[174:177], v226 offset:2048
	ds_read_b128 v[178:181], v226 offset:3072
	ds_read_b128 v[182:185], v226 offset:4096
	ds_read_b128 v[186:189], v226 offset:5120
	ds_read_b128 v[190:193], v226 offset:6144
	ds_read_b128 v[236:239], v226 offset:7168
	global_load_lds_dwordx4 v[240:241], off
	v_lshl_add_u64 v[240:241], v[164:165], 0, s[34:35]
	s_mov_b32 m0, s67
	s_nop 0
	global_load_lds_dwordx4 v[240:241], off
	s_waitcnt vmcnt(8)
	s_waitcnt lgkmcnt(0)
	s_barrier
	s_waitcnt lgkmcnt(0)
	v_mfma_i32_16x16x64_i8 v[142:145], v[158:161], v[166:169], v[142:145]
	v_mfma_i32_16x16x64_i8 v[142:145], v[154:157], v[170:173], v[142:145]
	v_mfma_i32_16x16x64_i8 v[138:141], v[150:153], v[166:169], v[138:141]
	v_mfma_i32_16x16x64_i8 v[138:141], v[146:149], v[170:173], v[138:141]
	v_mfma_i32_16x16x64_i8 v[126:129], v[158:161], v[174:177], v[126:129]
	v_mfma_i32_16x16x64_i8 v[126:129], v[154:157], v[178:181], v[126:129]
	v_mfma_i32_16x16x64_i8 v[122:125], v[150:153], v[174:177], v[122:125]
	v_mfma_i32_16x16x64_i8 v[122:125], v[146:149], v[178:181], v[122:125]
	v_mfma_i32_16x16x64_i8 v[110:113], v[158:161], v[182:185], v[110:113]
	v_mfma_i32_16x16x64_i8 v[110:113], v[154:157], v[186:189], v[110:113]
	v_mfma_i32_16x16x64_i8 v[106:109], v[150:153], v[182:185], v[106:109]
	v_mfma_i32_16x16x64_i8 v[106:109], v[146:149], v[186:189], v[106:109]
	v_mfma_i32_16x16x64_i8 v[94:97], v[158:161], v[190:193], v[94:97]
	v_mfma_i32_16x16x64_i8 v[94:97], v[154:157], v[236:239], v[94:97]
	v_mfma_i32_16x16x64_i8 v[90:93], v[150:153], v[190:193], v[90:93]
	v_mfma_i32_16x16x64_i8 v[90:93], v[146:149], v[236:239], v[90:93]
	v_mfma_i32_16x16x64_i8 v[134:137], v[62:65], v[166:169], v[134:137]
	v_mfma_i32_16x16x64_i8 v[134:137], v[58:61], v[170:173], v[134:137]
	v_mfma_i32_16x16x64_i8 v[130:133], v[54:57], v[166:169], v[130:133]
	v_mfma_i32_16x16x64_i8 v[130:133], v[50:53], v[170:173], v[130:133]
	v_mfma_i32_16x16x64_i8 v[118:121], v[62:65], v[174:177], v[118:121]
	v_mfma_i32_16x16x64_i8 v[118:121], v[58:61], v[178:181], v[118:121]
	v_mfma_i32_16x16x64_i8 v[114:117], v[54:57], v[174:177], v[114:117]
	v_mfma_i32_16x16x64_i8 v[114:117], v[50:53], v[178:181], v[114:117]
	v_mfma_i32_16x16x64_i8 v[102:105], v[62:65], v[182:185], v[102:105]
	v_mfma_i32_16x16x64_i8 v[102:105], v[58:61], v[186:189], v[102:105]
	v_mfma_i32_16x16x64_i8 v[98:101], v[54:57], v[182:185], v[98:101]
	v_mfma_i32_16x16x64_i8 v[98:101], v[50:53], v[186:189], v[98:101]
	v_mfma_i32_16x16x64_i8 v[86:89], v[62:65], v[190:193], v[86:89]
	v_mfma_i32_16x16x64_i8 v[86:89], v[58:61], v[236:239], v[86:89]
	v_mfma_i32_16x16x64_i8 v[82:85], v[54:57], v[190:193], v[82:85]
	v_mfma_i32_16x16x64_i8 v[82:85], v[50:53], v[236:239], v[82:85]
	s_barrier
	s_add_i32 s68, s60, s21
	s_add_i32 s69, s68, 0x2000
	v_lshl_add_u64 v[166:167], s[38:39], 0, v[202:203]
	s_mov_b32 m0, s68
	s_add_u32 s14, s38, 0x80000
	ds_read_b128 v[174:177], v226 offset:16384
	ds_read_b128 v[178:181], v226 offset:17408
	ds_read_b128 v[182:185], v226 offset:18432
	ds_read_b128 v[186:189], v226 offset:19456
	ds_read_b128 v[190:193], v226 offset:20480
	ds_read_b128 v[236:239], v226 offset:21504
	ds_read_b128 v[240:243], v226 offset:22528
	ds_read_b128 v[244:247], v226 offset:23552
	global_load_lds_dwordx4 v[166:167], off
	v_lshl_add_u64 v[168:169], s[38:39], 0, v[206:207]
	s_mov_b32 m0, s69
	s_addc_u32 s15, s39, 0
	s_add_i32 s70, s61, s21
	global_load_lds_dwordx4 v[168:169], off
	v_lshl_add_u64 v[170:171], s[14:15], 0, v[202:203]
	s_mov_b32 m0, s70
	s_add_i32 s71, s70, 0x2000
	global_load_lds_dwordx4 v[170:171], off
	v_lshl_add_u64 v[170:171], s[14:15], 0, v[206:207]
	s_mov_b32 m0, s71
	v_lshl_add_u64 v[172:173], s[40:41], 0, v[204:205]
	global_load_lds_dwordx4 v[170:171], off
	v_lshl_add_u64 v[170:171], s[40:41], 0, v[194:195]
	s_mov_b32 m0, s23
	s_nop 0
	global_load_lds_dwordx4 v[170:171], off
	s_mov_b32 m0, s42
	s_nop 0
	global_load_lds_dwordx4 v[172:173], off
	s_waitcnt vmcnt(8)
	s_waitcnt lgkmcnt(0)
	s_barrier
	s_waitcnt lgkmcnt(0)
	v_mfma_i32_16x16x64_i8 v[78:81], v[158:161], v[174:177], v[78:81]
	v_mfma_i32_16x16x64_i8 v[78:81], v[154:157], v[178:181], v[78:81]
	v_mfma_i32_16x16x64_i8 v[74:77], v[150:153], v[174:177], v[74:77]
	v_mfma_i32_16x16x64_i8 v[74:77], v[146:149], v[178:181], v[74:77]
	v_mfma_i32_16x16x64_i8 v[46:49], v[158:161], v[182:185], v[46:49]
	v_mfma_i32_16x16x64_i8 v[46:49], v[154:157], v[186:189], v[46:49]
	v_mfma_i32_16x16x64_i8 v[42:45], v[150:153], v[182:185], v[42:45]
	v_mfma_i32_16x16x64_i8 v[42:45], v[146:149], v[186:189], v[42:45]
	v_mfma_i32_16x16x64_i8 v[30:33], v[158:161], v[190:193], v[30:33]
	v_mfma_i32_16x16x64_i8 v[30:33], v[154:157], v[236:239], v[30:33]
	v_mfma_i32_16x16x64_i8 v[26:29], v[150:153], v[190:193], v[26:29]
	v_mfma_i32_16x16x64_i8 v[26:29], v[146:149], v[236:239], v[26:29]
	v_mfma_i32_16x16x64_i8 v[14:17], v[158:161], v[240:243], v[14:17]
	v_mfma_i32_16x16x64_i8 v[14:17], v[154:157], v[244:247], v[14:17]
	v_mfma_i32_16x16x64_i8 v[10:13], v[150:153], v[240:243], v[10:13]
	v_mfma_i32_16x16x64_i8 v[10:13], v[146:149], v[244:247], v[10:13]
	v_mfma_i32_16x16x64_i8 v[70:73], v[62:65], v[174:177], v[70:73]
	v_mfma_i32_16x16x64_i8 v[70:73], v[58:61], v[178:181], v[70:73]
	v_mfma_i32_16x16x64_i8 v[66:69], v[54:57], v[174:177], v[66:69]
	v_mfma_i32_16x16x64_i8 v[66:69], v[50:53], v[178:181], v[66:69]
	v_mfma_i32_16x16x64_i8 v[38:41], v[62:65], v[182:185], v[38:41]
	v_mfma_i32_16x16x64_i8 v[38:41], v[58:61], v[186:189], v[38:41]
	v_mfma_i32_16x16x64_i8 v[34:37], v[54:57], v[182:185], v[34:37]
	v_mfma_i32_16x16x64_i8 v[34:37], v[50:53], v[186:189], v[34:37]
	v_mfma_i32_16x16x64_i8 v[22:25], v[62:65], v[190:193], v[22:25]
	v_mfma_i32_16x16x64_i8 v[22:25], v[58:61], v[236:239], v[22:25]
	v_mfma_i32_16x16x64_i8 v[18:21], v[54:57], v[190:193], v[18:21]
	v_mfma_i32_16x16x64_i8 v[18:21], v[50:53], v[236:239], v[18:21]
	v_mfma_i32_16x16x64_i8 v[6:9], v[62:65], v[240:243], v[6:9]
	v_mfma_i32_16x16x64_i8 v[6:9], v[58:61], v[244:247], v[6:9]
	v_mfma_i32_16x16x64_i8 v[2:5], v[54:57], v[240:243], v[2:5]
	v_mfma_i32_16x16x64_i8 v[2:5], v[50:53], v[244:247], v[2:5]
	s_barrier
	s_add_i32 s72, 0, 0x18000
	v_add_u32_e32 v235, s72, v225
	s_add_i32 s74, 0, 0x1c000
	v_add_u32_e32 v236, s74, v225
	ds_read_b128 v[50:53], v235
	ds_read_b128 v[54:57], v235 offset:1024
	ds_read_b128 v[58:61], v235 offset:2048
	ds_read_b128 v[62:65], v235 offset:3072
	ds_read_b128 v[146:149], v236
	ds_read_b128 v[150:153], v236 offset:1024
	ds_read_b128 v[154:157], v236 offset:2048
	ds_read_b128 v[158:161], v236 offset:3072
	s_add_u32 s14, s40, 0x80000
	s_addc_u32 s15, s41, 0
	s_mov_b32 m0, s43
	v_lshl_add_u64 v[250:251], s[14:15], 0, v[194:195]
	ds_read_b128 v[174:177], v226 offset:32768
	ds_read_b128 v[178:181], v226 offset:33792
	ds_read_b128 v[182:185], v226 offset:34816
	ds_read_b128 v[186:189], v226 offset:35840
	ds_read_b128 v[190:193], v226 offset:36864
	ds_read_b128 v[238:241], v226 offset:37888
	ds_read_b128 v[242:245], v226 offset:38912
	ds_read_b128 v[246:249], v226 offset:39936
	global_load_lds_dwordx4 v[250:251], off
	v_lshl_add_u64 v[250:251], s[14:15], 0, v[204:205]
	s_mov_b32 m0, s44
	s_nop 0
	global_load_lds_dwordx4 v[250:251], off
	s_waitcnt vmcnt(8)
	s_waitcnt lgkmcnt(0)
	s_barrier
	s_waitcnt lgkmcnt(0)
	v_mfma_i32_16x16x64_i8 v[142:145], v[50:53], v[174:177], v[142:145]
	v_mfma_i32_16x16x64_i8 v[142:145], v[54:57], v[178:181], v[142:145]
	v_mfma_i32_16x16x64_i8 v[138:141], v[58:61], v[174:177], v[138:141]
	v_mfma_i32_16x16x64_i8 v[138:141], v[62:65], v[178:181], v[138:141]
	v_mfma_i32_16x16x64_i8 v[126:129], v[50:53], v[182:185], v[126:129]
	v_mfma_i32_16x16x64_i8 v[126:129], v[54:57], v[186:189], v[126:129]
	v_mfma_i32_16x16x64_i8 v[122:125], v[58:61], v[182:185], v[122:125]
	v_mfma_i32_16x16x64_i8 v[122:125], v[62:65], v[186:189], v[122:125]
	v_mfma_i32_16x16x64_i8 v[110:113], v[50:53], v[190:193], v[110:113]
	v_mfma_i32_16x16x64_i8 v[110:113], v[54:57], v[238:241], v[110:113]
	v_mfma_i32_16x16x64_i8 v[106:109], v[58:61], v[190:193], v[106:109]
	v_mfma_i32_16x16x64_i8 v[106:109], v[62:65], v[238:241], v[106:109]
	v_mfma_i32_16x16x64_i8 v[94:97], v[50:53], v[242:245], v[94:97]
	v_mfma_i32_16x16x64_i8 v[94:97], v[54:57], v[246:249], v[94:97]
	v_mfma_i32_16x16x64_i8 v[90:93], v[58:61], v[242:245], v[90:93]
	v_mfma_i32_16x16x64_i8 v[90:93], v[62:65], v[246:249], v[90:93]
	v_mfma_i32_16x16x64_i8 v[134:137], v[146:149], v[174:177], v[134:137]
	v_mfma_i32_16x16x64_i8 v[134:137], v[150:153], v[178:181], v[134:137]
	v_mfma_i32_16x16x64_i8 v[130:133], v[154:157], v[174:177], v[130:133]
	v_mfma_i32_16x16x64_i8 v[130:133], v[158:161], v[178:181], v[130:133]
	v_mfma_i32_16x16x64_i8 v[118:121], v[146:149], v[182:185], v[118:121]
	v_mfma_i32_16x16x64_i8 v[118:121], v[150:153], v[186:189], v[118:121]
	v_mfma_i32_16x16x64_i8 v[114:117], v[154:157], v[182:185], v[114:117]
	v_mfma_i32_16x16x64_i8 v[114:117], v[158:161], v[186:189], v[114:117]
	v_mfma_i32_16x16x64_i8 v[102:105], v[146:149], v[190:193], v[102:105]
	v_mfma_i32_16x16x64_i8 v[102:105], v[150:153], v[238:241], v[102:105]
	v_mfma_i32_16x16x64_i8 v[98:101], v[154:157], v[190:193], v[98:101]
	v_mfma_i32_16x16x64_i8 v[98:101], v[158:161], v[238:241], v[98:101]
	v_mfma_i32_16x16x64_i8 v[86:89], v[146:149], v[242:245], v[86:89]
	v_mfma_i32_16x16x64_i8 v[86:89], v[150:153], v[246:249], v[86:89]
	v_mfma_i32_16x16x64_i8 v[82:85], v[154:157], v[242:245], v[82:85]
	v_mfma_i32_16x16x64_i8 v[82:85], v[158:161], v[246:249], v[82:85]
	s_barrier
	s_add_i32 s72, s72, s21
	s_add_i32 s73, s72, 0x2000
	v_lshl_add_u64 v[166:167], v[166:167], 0, s[6:7]
	s_mov_b32 m0, s72
	s_add_u32 s14, s38, 0x80080
	ds_read_b128 v[174:177], v226 offset:49152
	ds_read_b128 v[178:181], v226 offset:50176
	ds_read_b128 v[182:185], v226 offset:51200
	ds_read_b128 v[186:189], v226 offset:52224
	ds_read_b128 v[190:193], v226 offset:53248
	ds_read_b128 v[238:241], v226 offset:54272
	ds_read_b128 v[242:245], v226 offset:55296
	ds_read_b128 v[246:249], v226 offset:56320
	global_load_lds_dwordx4 v[166:167], off
	v_lshl_add_u64 v[166:167], v[168:169], 0, s[6:7]
	s_mov_b32 m0, s73
	s_addc_u32 s15, s39, 0
	s_add_i32 s74, s74, s21
	global_load_lds_dwordx4 v[166:167], off
	v_lshl_add_u64 v[166:167], s[14:15], 0, v[202:203]
	s_mov_b32 m0, s74
	s_add_i32 s75, s74, 0x2000
	global_load_lds_dwordx4 v[166:167], off
	v_lshl_add_u64 v[166:167], s[14:15], 0, v[206:207]
	s_mov_b32 m0, s75
	s_nop 0
	global_load_lds_dwordx4 v[166:167], off
	v_lshl_add_u64 v[166:167], v[170:171], 0, s[6:7]
	s_mov_b32 m0, s51
	s_nop 0
	global_load_lds_dwordx4 v[166:167], off
	v_lshl_add_u64 v[166:167], v[172:173], 0, s[6:7]
	s_mov_b32 m0, s53
	s_nop 0
	global_load_lds_dwordx4 v[166:167], off
	s_waitcnt vmcnt(8)
	s_waitcnt lgkmcnt(0)
	s_barrier
	s_waitcnt lgkmcnt(0)
	v_mfma_i32_16x16x64_i8 v[78:81], v[50:53], v[174:177], v[78:81]
	v_mfma_i32_16x16x64_i8 v[78:81], v[54:57], v[178:181], v[78:81]
	v_mfma_i32_16x16x64_i8 v[74:77], v[58:61], v[174:177], v[74:77]
	v_mfma_i32_16x16x64_i8 v[74:77], v[62:65], v[178:181], v[74:77]
	v_mfma_i32_16x16x64_i8 v[46:49], v[50:53], v[182:185], v[46:49]
	v_mfma_i32_16x16x64_i8 v[46:49], v[54:57], v[186:189], v[46:49]
	v_mfma_i32_16x16x64_i8 v[42:45], v[58:61], v[182:185], v[42:45]
	v_mfma_i32_16x16x64_i8 v[42:45], v[62:65], v[186:189], v[42:45]
	v_mfma_i32_16x16x64_i8 v[30:33], v[50:53], v[190:193], v[30:33]
	v_mfma_i32_16x16x64_i8 v[30:33], v[54:57], v[238:241], v[30:33]
	v_mfma_i32_16x16x64_i8 v[26:29], v[58:61], v[190:193], v[26:29]
	v_mfma_i32_16x16x64_i8 v[26:29], v[62:65], v[238:241], v[26:29]
	v_mfma_i32_16x16x64_i8 v[14:17], v[50:53], v[242:245], v[14:17]
	v_mfma_i32_16x16x64_i8 v[14:17], v[54:57], v[246:249], v[14:17]
	v_mfma_i32_16x16x64_i8 v[10:13], v[58:61], v[242:245], v[10:13]
	v_mfma_i32_16x16x64_i8 v[10:13], v[62:65], v[246:249], v[10:13]
	v_mfma_i32_16x16x64_i8 v[70:73], v[146:149], v[174:177], v[70:73]
	v_mfma_i32_16x16x64_i8 v[70:73], v[150:153], v[178:181], v[70:73]
	v_mfma_i32_16x16x64_i8 v[66:69], v[154:157], v[174:177], v[66:69]
	v_mfma_i32_16x16x64_i8 v[66:69], v[158:161], v[178:181], v[66:69]
	v_mfma_i32_16x16x64_i8 v[38:41], v[146:149], v[182:185], v[38:41]
	v_mfma_i32_16x16x64_i8 v[38:41], v[150:153], v[186:189], v[38:41]
	v_mfma_i32_16x16x64_i8 v[34:37], v[154:157], v[182:185], v[34:37]
	v_mfma_i32_16x16x64_i8 v[34:37], v[158:161], v[186:189], v[34:37]
	v_mfma_i32_16x16x64_i8 v[22:25], v[146:149], v[190:193], v[22:25]
	v_mfma_i32_16x16x64_i8 v[22:25], v[150:153], v[238:241], v[22:25]
	v_mfma_i32_16x16x64_i8 v[18:21], v[154:157], v[190:193], v[18:21]
	v_mfma_i32_16x16x64_i8 v[18:21], v[158:161], v[238:241], v[18:21]
	v_mfma_i32_16x16x64_i8 v[6:9], v[146:149], v[242:245], v[6:9]
	v_mfma_i32_16x16x64_i8 v[6:9], v[150:153], v[246:249], v[6:9]
	v_mfma_i32_16x16x64_i8 v[2:5], v[154:157], v[242:245], v[2:5]
	v_mfma_i32_16x16x64_i8 v[2:5], v[158:161], v[246:249], v[2:5]
	s_barrier
	s_add_i32 s3, s3, 2
	s_add_u32 s34, s34, 0x100
	s_addc_u32 s35, s35, 0
	s_cmp_gt_u32 s3, 29
	s_cbranch_scc0 .LBB0_734
	s_nop 15
	s_nop 15
	s_and_b64 vcc, exec, s[8:9]
	s_cbranch_vccz .LBB0_737
	s_barrier

.LBB0_740:
	ds_read_b128 v[158:161], v227
	ds_read_b128 v[154:157], v227 offset:1024
	ds_read_b128 v[150:153], v227 offset:2048
	ds_read_b128 v[146:149], v227 offset:3072
	ds_read_b128 v[62:65], v233
	ds_read_b128 v[58:61], v233 offset:1024
	ds_read_b128 v[54:57], v233 offset:2048
	ds_read_b128 v[50:53], v233 offset:3072
	s_add_u32 s36, s38, 0xfff80080
	s_addc_u32 s37, s39, -1
	s_cmp_eq_u32 s33, 28
	s_cselect_b32 s41, s1, s37
	s_cselect_b32 s40, s0, s36
	s_cselect_b32 s37, s15, s29
	s_cselect_b32 s36, s14, s25
	s_mov_b32 m0, s66
	v_lshl_add_u64 v[238:239], s[38:39], 0, v[208:209]
	ds_read_b128 v[162:165], v226
	ds_read_b128 v[166:169], v226 offset:1024
	ds_read_b128 v[170:173], v226 offset:2048
	ds_read_b128 v[174:177], v226 offset:3072
	ds_read_b128 v[178:181], v226 offset:4096
	ds_read_b128 v[182:185], v226 offset:5120
	ds_read_b128 v[186:189], v226 offset:6144
	ds_read_b128 v[190:193], v226 offset:7168
	global_load_lds_dwordx4 v[238:239], off
	v_lshl_add_u64 v[238:239], s[38:39], 0, v[212:213]
	s_mov_b32 m0, s67
	s_nop 0
	global_load_lds_dwordx4 v[238:239], off
	s_waitcnt vmcnt(8)
	s_waitcnt lgkmcnt(0)
	s_barrier
	s_waitcnt lgkmcnt(0)
	v_mfma_i32_16x16x64_i8 v[142:145], v[158:161], v[162:165], v[142:145]
	v_mfma_i32_16x16x64_i8 v[142:145], v[154:157], v[166:169], v[142:145]
	v_mfma_i32_16x16x64_i8 v[138:141], v[150:153], v[162:165], v[138:141]
	v_mfma_i32_16x16x64_i8 v[138:141], v[146:149], v[166:169], v[138:141]
	v_mfma_i32_16x16x64_i8 v[126:129], v[158:161], v[170:173], v[126:129]
	v_mfma_i32_16x16x64_i8 v[126:129], v[154:157], v[174:177], v[126:129]
	v_mfma_i32_16x16x64_i8 v[122:125], v[150:153], v[170:173], v[122:125]
	v_mfma_i32_16x16x64_i8 v[122:125], v[146:149], v[174:177], v[122:125]
	v_mfma_i32_16x16x64_i8 v[110:113], v[158:161], v[178:181], v[110:113]
	v_mfma_i32_16x16x64_i8 v[110:113], v[154:157], v[182:185], v[110:113]
	v_mfma_i32_16x16x64_i8 v[106:109], v[150:153], v[178:181], v[106:109]
	v_mfma_i32_16x16x64_i8 v[106:109], v[146:149], v[182:185], v[106:109]
	v_mfma_i32_16x16x64_i8 v[94:97], v[158:161], v[186:189], v[94:97]
	v_mfma_i32_16x16x64_i8 v[94:97], v[154:157], v[190:193], v[94:97]
	v_mfma_i32_16x16x64_i8 v[90:93], v[150:153], v[186:189], v[90:93]
	v_mfma_i32_16x16x64_i8 v[90:93], v[146:149], v[190:193], v[90:93]
	v_mfma_i32_16x16x64_i8 v[134:137], v[62:65], v[162:165], v[134:137]
	v_mfma_i32_16x16x64_i8 v[134:137], v[58:61], v[166:169], v[134:137]
	v_mfma_i32_16x16x64_i8 v[130:133], v[54:57], v[162:165], v[130:133]
	v_mfma_i32_16x16x64_i8 v[130:133], v[50:53], v[166:169], v[130:133]
	v_mfma_i32_16x16x64_i8 v[118:121], v[62:65], v[170:173], v[118:121]
	v_mfma_i32_16x16x64_i8 v[118:121], v[58:61], v[174:177], v[118:121]
	v_mfma_i32_16x16x64_i8 v[114:117], v[54:57], v[170:173], v[114:117]
	v_mfma_i32_16x16x64_i8 v[114:117], v[50:53], v[174:177], v[114:117]
	v_mfma_i32_16x16x64_i8 v[102:105], v[62:65], v[178:181], v[102:105]
	v_mfma_i32_16x16x64_i8 v[102:105], v[58:61], v[182:185], v[102:105]
	v_mfma_i32_16x16x64_i8 v[98:101], v[54:57], v[178:181], v[98:101]
	v_mfma_i32_16x16x64_i8 v[98:101], v[50:53], v[182:185], v[98:101]
	v_mfma_i32_16x16x64_i8 v[86:89], v[62:65], v[186:189], v[86:89]
	v_mfma_i32_16x16x64_i8 v[86:89], v[58:61], v[190:193], v[86:89]
	v_mfma_i32_16x16x64_i8 v[82:85], v[54:57], v[186:189], v[82:85]
	v_mfma_i32_16x16x64_i8 v[82:85], v[50:53], v[190:193], v[82:85]
	s_barrier
	s_mov_b32 m0, s68
	v_lshl_add_u64 v[162:163], s[36:37], 0, v[202:203]
	s_add_u32 s80, s36, 0x80000
	ds_read_b128 v[170:173], v226 offset:16384
	ds_read_b128 v[174:177], v226 offset:17408
	ds_read_b128 v[178:181], v226 offset:18432
	ds_read_b128 v[182:185], v226 offset:19456
	ds_read_b128 v[186:189], v226 offset:20480
	ds_read_b128 v[190:193], v226 offset:21504
	ds_read_b128 v[238:241], v226 offset:22528
	ds_read_b128 v[242:245], v226 offset:23552
	global_load_lds_dwordx4 v[162:163], off
	v_lshl_add_u64 v[164:165], s[36:37], 0, v[206:207]
	s_mov_b32 m0, s69
	s_addc_u32 s81, s37, 0
	global_load_lds_dwordx4 v[164:165], off
	v_lshl_add_u64 v[166:167], s[80:81], 0, v[202:203]
	s_mov_b32 m0, s70
	v_lshl_add_u64 v[168:169], s[40:41], 0, v[204:205]
	global_load_lds_dwordx4 v[166:167], off
	v_lshl_add_u64 v[166:167], s[80:81], 0, v[206:207]
	s_mov_b32 m0, s71
	s_nop 0
	global_load_lds_dwordx4 v[166:167], off
	v_lshl_add_u64 v[166:167], s[40:41], 0, v[194:195]
	s_mov_b32 m0, s23
	s_nop 0
	global_load_lds_dwordx4 v[166:167], off
	s_mov_b32 m0, s42
	s_nop 0
	global_load_lds_dwordx4 v[168:169], off
	s_waitcnt vmcnt(8)
	s_waitcnt lgkmcnt(0)
	s_barrier
	s_waitcnt lgkmcnt(0)
	v_mfma_i32_16x16x64_i8 v[78:81], v[158:161], v[170:173], v[78:81]
	v_mfma_i32_16x16x64_i8 v[78:81], v[154:157], v[174:177], v[78:81]
	v_mfma_i32_16x16x64_i8 v[74:77], v[150:153], v[170:173], v[74:77]
	v_mfma_i32_16x16x64_i8 v[74:77], v[146:149], v[174:177], v[74:77]
	v_mfma_i32_16x16x64_i8 v[46:49], v[158:161], v[178:181], v[46:49]
	v_mfma_i32_16x16x64_i8 v[46:49], v[154:157], v[182:185], v[46:49]
	v_mfma_i32_16x16x64_i8 v[42:45], v[150:153], v[178:181], v[42:45]
	v_mfma_i32_16x16x64_i8 v[42:45], v[146:149], v[182:185], v[42:45]
	v_mfma_i32_16x16x64_i8 v[30:33], v[158:161], v[186:189], v[30:33]
	v_mfma_i32_16x16x64_i8 v[30:33], v[154:157], v[190:193], v[30:33]
	v_mfma_i32_16x16x64_i8 v[26:29], v[150:153], v[186:189], v[26:29]
	v_mfma_i32_16x16x64_i8 v[26:29], v[146:149], v[190:193], v[26:29]
	v_mfma_i32_16x16x64_i8 v[14:17], v[158:161], v[238:241], v[14:17]
	v_mfma_i32_16x16x64_i8 v[14:17], v[154:157], v[242:245], v[14:17]
	v_mfma_i32_16x16x64_i8 v[10:13], v[150:153], v[238:241], v[10:13]
	v_mfma_i32_16x16x64_i8 v[10:13], v[146:149], v[242:245], v[10:13]
	v_mfma_i32_16x16x64_i8 v[70:73], v[62:65], v[170:173], v[70:73]
	v_mfma_i32_16x16x64_i8 v[70:73], v[58:61], v[174:177], v[70:73]
	v_mfma_i32_16x16x64_i8 v[66:69], v[54:57], v[170:173], v[66:69]
	v_mfma_i32_16x16x64_i8 v[66:69], v[50:53], v[174:177], v[66:69]
	v_mfma_i32_16x16x64_i8 v[38:41], v[62:65], v[178:181], v[38:41]
	v_mfma_i32_16x16x64_i8 v[38:41], v[58:61], v[182:185], v[38:41]
	v_mfma_i32_16x16x64_i8 v[34:37], v[54:57], v[178:181], v[34:37]
	v_mfma_i32_16x16x64_i8 v[34:37], v[50:53], v[182:185], v[34:37]
	v_mfma_i32_16x16x64_i8 v[22:25], v[62:65], v[186:189], v[22:25]
	v_mfma_i32_16x16x64_i8 v[22:25], v[58:61], v[190:193], v[22:25]
	v_mfma_i32_16x16x64_i8 v[18:21], v[54:57], v[186:189], v[18:21]
	v_mfma_i32_16x16x64_i8 v[18:21], v[50:53], v[190:193], v[18:21]
	v_mfma_i32_16x16x64_i8 v[6:9], v[62:65], v[238:241], v[6:9]
	v_mfma_i32_16x16x64_i8 v[6:9], v[58:61], v[242:245], v[6:9]
	v_mfma_i32_16x16x64_i8 v[2:5], v[54:57], v[238:241], v[2:5]
	v_mfma_i32_16x16x64_i8 v[2:5], v[50:53], v[242:245], v[2:5]
	s_barrier
	ds_read_b128 v[50:53], v235
	ds_read_b128 v[54:57], v235 offset:1024
	ds_read_b128 v[58:61], v235 offset:2048
	ds_read_b128 v[62:65], v235 offset:3072
	ds_read_b128 v[146:149], v236
	ds_read_b128 v[150:153], v236 offset:1024
	ds_read_b128 v[154:157], v236 offset:2048
	ds_read_b128 v[158:161], v236 offset:3072
	s_add_u32 s40, s40, 0x80000
	s_addc_u32 s41, s41, 0
	s_mov_b32 m0, s43
	v_lshl_add_u64 v[246:247], s[40:41], 0, v[194:195]
	ds_read_b128 v[170:173], v226 offset:32768
	ds_read_b128 v[174:177], v226 offset:33792
	ds_read_b128 v[178:181], v226 offset:34816
	ds_read_b128 v[182:185], v226 offset:35840
	ds_read_b128 v[186:189], v226 offset:36864
	ds_read_b128 v[190:193], v226 offset:37888
	ds_read_b128 v[238:241], v226 offset:38912
	ds_read_b128 v[242:245], v226 offset:39936
	global_load_lds_dwordx4 v[246:247], off
	v_lshl_add_u64 v[246:247], s[40:41], 0, v[204:205]
	s_mov_b32 m0, s44
	s_nop 0
	global_load_lds_dwordx4 v[246:247], off
	s_waitcnt vmcnt(8)
	s_waitcnt lgkmcnt(0)
	s_barrier
	s_waitcnt lgkmcnt(0)
	v_mfma_i32_16x16x64_i8 v[142:145], v[50:53], v[170:173], v[142:145]
	v_mfma_i32_16x16x64_i8 v[142:145], v[54:57], v[174:177], v[142:145]
	v_mfma_i32_16x16x64_i8 v[138:141], v[58:61], v[170:173], v[138:141]
	v_mfma_i32_16x16x64_i8 v[138:141], v[62:65], v[174:177], v[138:141]
	v_mfma_i32_16x16x64_i8 v[126:129], v[50:53], v[178:181], v[126:129]
	v_mfma_i32_16x16x64_i8 v[126:129], v[54:57], v[182:185], v[126:129]
	v_mfma_i32_16x16x64_i8 v[122:125], v[58:61], v[178:181], v[122:125]
	v_mfma_i32_16x16x64_i8 v[122:125], v[62:65], v[182:185], v[122:125]
	v_mfma_i32_16x16x64_i8 v[110:113], v[50:53], v[186:189], v[110:113]
	v_mfma_i32_16x16x64_i8 v[110:113], v[54:57], v[190:193], v[110:113]
	v_mfma_i32_16x16x64_i8 v[106:109], v[58:61], v[186:189], v[106:109]
	v_mfma_i32_16x16x64_i8 v[106:109], v[62:65], v[190:193], v[106:109]
	v_mfma_i32_16x16x64_i8 v[94:97], v[50:53], v[238:241], v[94:97]
	v_mfma_i32_16x16x64_i8 v[94:97], v[54:57], v[242:245], v[94:97]
	v_mfma_i32_16x16x64_i8 v[90:93], v[58:61], v[238:241], v[90:93]
	v_mfma_i32_16x16x64_i8 v[90:93], v[62:65], v[242:245], v[90:93]
	v_mfma_i32_16x16x64_i8 v[134:137], v[146:149], v[170:173], v[134:137]
	v_mfma_i32_16x16x64_i8 v[134:137], v[150:153], v[174:177], v[134:137]
	v_mfma_i32_16x16x64_i8 v[130:133], v[154:157], v[170:173], v[130:133]
	v_mfma_i32_16x16x64_i8 v[130:133], v[158:161], v[174:177], v[130:133]
	v_mfma_i32_16x16x64_i8 v[118:121], v[146:149], v[178:181], v[118:121]
	v_mfma_i32_16x16x64_i8 v[118:121], v[150:153], v[182:185], v[118:121]
	v_mfma_i32_16x16x64_i8 v[114:117], v[154:157], v[178:181], v[114:117]
	v_mfma_i32_16x16x64_i8 v[114:117], v[158:161], v[182:185], v[114:117]
	v_mfma_i32_16x16x64_i8 v[102:105], v[146:149], v[186:189], v[102:105]
	v_mfma_i32_16x16x64_i8 v[102:105], v[150:153], v[190:193], v[102:105]
	v_mfma_i32_16x16x64_i8 v[98:101], v[154:157], v[186:189], v[98:101]
	v_mfma_i32_16x16x64_i8 v[98:101], v[158:161], v[190:193], v[98:101]
	v_mfma_i32_16x16x64_i8 v[86:89], v[146:149], v[238:241], v[86:89]
	v_mfma_i32_16x16x64_i8 v[86:89], v[150:153], v[242:245], v[86:89]
	v_mfma_i32_16x16x64_i8 v[82:85], v[154:157], v[238:241], v[82:85]
	v_mfma_i32_16x16x64_i8 v[82:85], v[158:161], v[242:245], v[82:85]
	s_barrier
	s_mov_b32 m0, s72
	v_lshl_add_u64 v[162:163], v[162:163], 0, s[6:7]
	s_add_u32 s36, s36, 0x80080
	ds_read_b128 v[170:173], v226 offset:49152
	ds_read_b128 v[174:177], v226 offset:50176
	ds_read_b128 v[178:181], v226 offset:51200
	ds_read_b128 v[182:185], v226 offset:52224
	ds_read_b128 v[186:189], v226 offset:53248
	ds_read_b128 v[190:193], v226 offset:54272
	ds_read_b128 v[238:241], v226 offset:55296
	ds_read_b128 v[242:245], v226 offset:56320
	global_load_lds_dwordx4 v[162:163], off
	v_lshl_add_u64 v[162:163], v[164:165], 0, s[6:7]
	s_mov_b32 m0, s73
	s_addc_u32 s37, s37, 0
	global_load_lds_dwordx4 v[162:163], off
	v_lshl_add_u64 v[162:163], s[36:37], 0, v[202:203]
	s_mov_b32 m0, s74
	s_nop 0
	global_load_lds_dwordx4 v[162:163], off
	v_lshl_add_u64 v[162:163], s[36:37], 0, v[206:207]
	s_mov_b32 m0, s75
	s_nop 0
	global_load_lds_dwordx4 v[162:163], off
	v_lshl_add_u64 v[162:163], v[166:167], 0, s[6:7]
	s_mov_b32 m0, s51
	s_nop 0
	global_load_lds_dwordx4 v[162:163], off
	v_lshl_add_u64 v[162:163], v[168:169], 0, s[6:7]
	s_mov_b32 m0, s53
	s_nop 0
	global_load_lds_dwordx4 v[162:163], off
	s_waitcnt vmcnt(8)
	s_waitcnt lgkmcnt(0)
	s_barrier
	s_waitcnt lgkmcnt(0)
	v_mfma_i32_16x16x64_i8 v[78:81], v[50:53], v[170:173], v[78:81]
	v_mfma_i32_16x16x64_i8 v[78:81], v[54:57], v[174:177], v[78:81]
	v_mfma_i32_16x16x64_i8 v[74:77], v[58:61], v[170:173], v[74:77]
	v_mfma_i32_16x16x64_i8 v[74:77], v[62:65], v[174:177], v[74:77]
	v_mfma_i32_16x16x64_i8 v[46:49], v[50:53], v[178:181], v[46:49]
	v_mfma_i32_16x16x64_i8 v[46:49], v[54:57], v[182:185], v[46:49]
	v_mfma_i32_16x16x64_i8 v[42:45], v[58:61], v[178:181], v[42:45]
	v_mfma_i32_16x16x64_i8 v[42:45], v[62:65], v[182:185], v[42:45]
	v_mfma_i32_16x16x64_i8 v[30:33], v[50:53], v[186:189], v[30:33]
	v_mfma_i32_16x16x64_i8 v[30:33], v[54:57], v[190:193], v[30:33]
	v_mfma_i32_16x16x64_i8 v[26:29], v[58:61], v[186:189], v[26:29]
	v_mfma_i32_16x16x64_i8 v[26:29], v[62:65], v[190:193], v[26:29]
	v_mfma_i32_16x16x64_i8 v[14:17], v[50:53], v[238:241], v[14:17]
	v_mfma_i32_16x16x64_i8 v[14:17], v[54:57], v[242:245], v[14:17]
	v_mfma_i32_16x16x64_i8 v[10:13], v[58:61], v[238:241], v[10:13]
	v_mfma_i32_16x16x64_i8 v[10:13], v[62:65], v[242:245], v[10:13]
	v_mfma_i32_16x16x64_i8 v[70:73], v[146:149], v[170:173], v[70:73]
	v_mfma_i32_16x16x64_i8 v[70:73], v[150:153], v[174:177], v[70:73]
	v_mfma_i32_16x16x64_i8 v[66:69], v[154:157], v[170:173], v[66:69]
	v_mfma_i32_16x16x64_i8 v[66:69], v[158:161], v[174:177], v[66:69]
	v_mfma_i32_16x16x64_i8 v[38:41], v[146:149], v[178:181], v[38:41]
	v_mfma_i32_16x16x64_i8 v[38:41], v[150:153], v[182:185], v[38:41]
	v_mfma_i32_16x16x64_i8 v[34:37], v[154:157], v[178:181], v[34:37]
	v_mfma_i32_16x16x64_i8 v[34:37], v[158:161], v[182:185], v[34:37]
	v_mfma_i32_16x16x64_i8 v[22:25], v[146:149], v[186:189], v[22:25]
	v_mfma_i32_16x16x64_i8 v[22:25], v[150:153], v[190:193], v[22:25]
	v_mfma_i32_16x16x64_i8 v[18:21], v[154:157], v[186:189], v[18:21]
	v_mfma_i32_16x16x64_i8 v[18:21], v[158:161], v[190:193], v[18:21]
	v_mfma_i32_16x16x64_i8 v[6:9], v[146:149], v[238:241], v[6:9]
	v_mfma_i32_16x16x64_i8 v[6:9], v[150:153], v[242:245], v[6:9]
	v_mfma_i32_16x16x64_i8 v[2:5], v[154:157], v[238:241], v[2:5]
	v_mfma_i32_16x16x64_i8 v[2:5], v[158:161], v[242:245], v[2:5]
	s_barrier
	s_add_i32 s33, s33, 2
	s_add_u32 s38, s38, 0x100
	s_addc_u32 s39, s39, 0
	s_add_u32 s25, s25, 0x100
	s_addc_u32 s29, s29, 0
	s_cmp_gt_u32 s33, 29
	s_cbranch_scc0 .LBB0_740
	s_nop 15
	s_nop 15
	s_and_b64 vcc, exec, s[8:9]
	s_cbranch_vccz .LBB0_743
	s_barrier

.LBB0_746:
	ds_read_b128 v[158:161], v227
	ds_read_b128 v[154:157], v227 offset:1024
	ds_read_b128 v[150:153], v227 offset:2048
	ds_read_b128 v[146:149], v227 offset:3072
	ds_read_b128 v[142:145], v233
	ds_read_b128 v[138:141], v233 offset:1024
	ds_read_b128 v[134:137], v233 offset:2048
	ds_read_b128 v[130:133], v233 offset:3072
	s_add_u32 s38, s29, s36
	s_addc_u32 s39, s33, s37
	s_add_u32 s38, s38, 0x3d000100
	s_addc_u32 s39, s39, 0
	s_add_u32 s81, s25, s36
	s_addc_u32 s82, s79, s37
	s_cmpk_eq_i32 s36, 0x700
	s_cselect_b32 s41, s1, s39
	s_cselect_b32 s40, s0, s38
	s_cselect_b32 s39, s15, s82
	s_cselect_b32 s38, s14, s81
	s_mov_b32 m0, s66
	v_lshl_add_u64 v[242:243], v[162:163], 0, s[36:37]
	ds_read_b128 v[166:169], v226
	ds_read_b128 v[170:173], v226 offset:1024
	ds_read_b128 v[174:177], v226 offset:2048
	ds_read_b128 v[178:181], v226 offset:3072
	ds_read_b128 v[182:185], v226 offset:4096
	ds_read_b128 v[186:189], v226 offset:5120
	ds_read_b128 v[190:193], v226 offset:6144
	ds_read_b128 v[238:241], v226 offset:7168
	global_load_lds_dwordx4 v[242:243], off
	v_lshl_add_u64 v[242:243], v[164:165], 0, s[36:37]
	s_mov_b32 m0, s67
	s_nop 0
	global_load_lds_dwordx4 v[242:243], off
	s_waitcnt vmcnt(8)
	s_waitcnt lgkmcnt(0)
	s_barrier
	s_waitcnt lgkmcnt(0)
	v_mfma_i32_16x16x64_i8 v[30:33], v[158:161], v[166:169], v[30:33]
	v_mfma_i32_16x16x64_i8 v[30:33], v[154:157], v[170:173], v[30:33]
	v_mfma_i32_16x16x64_i8 v[26:29], v[150:153], v[166:169], v[26:29]
	v_mfma_i32_16x16x64_i8 v[26:29], v[146:149], v[170:173], v[26:29]
	v_mfma_i32_16x16x64_i8 v[46:49], v[158:161], v[174:177], v[46:49]
	v_mfma_i32_16x16x64_i8 v[46:49], v[154:157], v[178:181], v[46:49]
	v_mfma_i32_16x16x64_i8 v[42:45], v[150:153], v[174:177], v[42:45]
	v_mfma_i32_16x16x64_i8 v[42:45], v[146:149], v[178:181], v[42:45]
	v_mfma_i32_16x16x64_i8 v[74:77], v[158:161], v[182:185], v[74:77]
	v_mfma_i32_16x16x64_i8 v[74:77], v[154:157], v[186:189], v[74:77]
	v_mfma_i32_16x16x64_i8 v[70:73], v[150:153], v[182:185], v[70:73]
	v_mfma_i32_16x16x64_i8 v[70:73], v[146:149], v[186:189], v[70:73]
	v_mfma_i32_16x16x64_i8 v[94:97], v[158:161], v[190:193], v[94:97]
	v_mfma_i32_16x16x64_i8 v[94:97], v[154:157], v[238:241], v[94:97]
	v_mfma_i32_16x16x64_i8 v[90:93], v[150:153], v[190:193], v[90:93]
	v_mfma_i32_16x16x64_i8 v[90:93], v[146:149], v[238:241], v[90:93]
	v_mfma_i32_16x16x64_i8 v[38:41], v[142:145], v[166:169], v[38:41]
	v_mfma_i32_16x16x64_i8 v[38:41], v[138:141], v[170:173], v[38:41]
	v_mfma_i32_16x16x64_i8 v[34:37], v[134:137], v[166:169], v[34:37]
	v_mfma_i32_16x16x64_i8 v[34:37], v[130:133], v[170:173], v[34:37]
	v_mfma_i32_16x16x64_i8 v[58:61], v[142:145], v[174:177], v[58:61]
	v_mfma_i32_16x16x64_i8 v[58:61], v[138:141], v[178:181], v[58:61]
	v_mfma_i32_16x16x64_i8 v[54:57], v[134:137], v[174:177], v[54:57]
	v_mfma_i32_16x16x64_i8 v[54:57], v[130:133], v[178:181], v[54:57]
	v_mfma_i32_16x16x64_i8 v[86:89], v[142:145], v[182:185], v[86:89]
	v_mfma_i32_16x16x64_i8 v[86:89], v[138:141], v[186:189], v[86:89]
	v_mfma_i32_16x16x64_i8 v[82:85], v[134:137], v[182:185], v[82:85]
	v_mfma_i32_16x16x64_i8 v[82:85], v[130:133], v[186:189], v[82:85]
	v_mfma_i32_16x16x64_i8 v[102:105], v[142:145], v[190:193], v[102:105]
	v_mfma_i32_16x16x64_i8 v[102:105], v[138:141], v[238:241], v[102:105]
	v_mfma_i32_16x16x64_i8 v[98:101], v[134:137], v[190:193], v[98:101]
	v_mfma_i32_16x16x64_i8 v[98:101], v[130:133], v[238:241], v[98:101]
	s_barrier
	s_mov_b32 m0, s68
	v_lshl_add_u64 v[166:167], s[38:39], 0, v[202:203]
	s_add_u32 s82, s38, 0x80000
	ds_read_b128 v[174:177], v226 offset:16384
	ds_read_b128 v[178:181], v226 offset:17408
	ds_read_b128 v[182:185], v226 offset:18432
	ds_read_b128 v[186:189], v226 offset:19456
	ds_read_b128 v[190:193], v226 offset:20480
	ds_read_b128 v[238:241], v226 offset:21504
	ds_read_b128 v[242:245], v226 offset:22528
	ds_read_b128 v[246:249], v226 offset:23552
	global_load_lds_dwordx4 v[166:167], off
	v_lshl_add_u64 v[168:169], s[38:39], 0, v[206:207]
	s_mov_b32 m0, s69
	s_addc_u32 s83, s39, 0
	global_load_lds_dwordx4 v[168:169], off
	v_lshl_add_u64 v[170:171], s[82:83], 0, v[202:203]
	s_mov_b32 m0, s70
	v_lshl_add_u64 v[172:173], s[40:41], 0, v[204:205]
	global_load_lds_dwordx4 v[170:171], off
	v_lshl_add_u64 v[170:171], s[82:83], 0, v[206:207]
	s_mov_b32 m0, s71
	s_nop 0
	global_load_lds_dwordx4 v[170:171], off
	v_lshl_add_u64 v[170:171], s[40:41], 0, v[194:195]
	s_mov_b32 m0, s23
	s_nop 0
	global_load_lds_dwordx4 v[170:171], off
	s_mov_b32 m0, s42
	s_nop 0
	global_load_lds_dwordx4 v[172:173], off
	s_waitcnt vmcnt(8)
	s_waitcnt lgkmcnt(0)
	s_barrier
	s_waitcnt lgkmcnt(0)
	v_mfma_i32_16x16x64_i8 v[110:113], v[158:161], v[174:177], v[110:113]
	v_mfma_i32_16x16x64_i8 v[110:113], v[154:157], v[178:181], v[110:113]
	v_mfma_i32_16x16x64_i8 v[106:109], v[150:153], v[174:177], v[106:109]
	v_mfma_i32_16x16x64_i8 v[106:109], v[146:149], v[178:181], v[106:109]
	v_mfma_i32_16x16x64_i8 v[126:129], v[158:161], v[182:185], v[126:129]
	v_mfma_i32_16x16x64_i8 v[126:129], v[154:157], v[186:189], v[126:129]
	v_mfma_i32_16x16x64_i8 v[118:121], v[150:153], v[182:185], v[118:121]
	v_mfma_i32_16x16x64_i8 v[118:121], v[146:149], v[186:189], v[118:121]
	v_mfma_i32_16x16x64_i8 v[62:65], v[158:161], v[190:193], v[62:65]
	v_mfma_i32_16x16x64_i8 v[62:65], v[154:157], v[238:241], v[62:65]
	v_mfma_i32_16x16x64_i8 v[50:53], v[150:153], v[190:193], v[50:53]
	v_mfma_i32_16x16x64_i8 v[50:53], v[146:149], v[238:241], v[50:53]
	v_mfma_i32_16x16x64_i8 v[14:17], v[158:161], v[242:245], v[14:17]
	v_mfma_i32_16x16x64_i8 v[14:17], v[154:157], v[246:249], v[14:17]
	v_mfma_i32_16x16x64_i8 v[10:13], v[150:153], v[242:245], v[10:13]
	v_mfma_i32_16x16x64_i8 v[10:13], v[146:149], v[246:249], v[10:13]
	v_mfma_i32_16x16x64_i8 v[122:125], v[142:145], v[174:177], v[122:125]
	v_mfma_i32_16x16x64_i8 v[122:125], v[138:141], v[178:181], v[122:125]
	v_mfma_i32_16x16x64_i8 v[114:117], v[134:137], v[174:177], v[114:117]
	v_mfma_i32_16x16x64_i8 v[114:117], v[130:133], v[178:181], v[114:117]
	v_mfma_i32_16x16x64_i8 v[78:81], v[142:145], v[182:185], v[78:81]
	v_mfma_i32_16x16x64_i8 v[78:81], v[138:141], v[186:189], v[78:81]
	v_mfma_i32_16x16x64_i8 v[66:69], v[134:137], v[182:185], v[66:69]
	v_mfma_i32_16x16x64_i8 v[66:69], v[130:133], v[186:189], v[66:69]
	v_mfma_i32_16x16x64_i8 v[22:25], v[142:145], v[190:193], v[22:25]
	v_mfma_i32_16x16x64_i8 v[22:25], v[138:141], v[238:241], v[22:25]
	v_mfma_i32_16x16x64_i8 v[18:21], v[134:137], v[190:193], v[18:21]
	v_mfma_i32_16x16x64_i8 v[18:21], v[130:133], v[238:241], v[18:21]
	v_mfma_i32_16x16x64_i8 v[6:9], v[142:145], v[242:245], v[6:9]
	v_mfma_i32_16x16x64_i8 v[6:9], v[138:141], v[246:249], v[6:9]
	v_mfma_i32_16x16x64_i8 v[2:5], v[134:137], v[242:245], v[2:5]
	v_mfma_i32_16x16x64_i8 v[2:5], v[130:133], v[246:249], v[2:5]
	s_barrier
	ds_read_b128 v[130:133], v235
	ds_read_b128 v[134:137], v235 offset:1024
	ds_read_b128 v[138:141], v235 offset:2048
	ds_read_b128 v[142:145], v235 offset:3072
	ds_read_b128 v[146:149], v236
	ds_read_b128 v[150:153], v236 offset:1024
	ds_read_b128 v[154:157], v236 offset:2048
	ds_read_b128 v[158:161], v236 offset:3072
	s_add_u32 s40, s40, 0x80000
	s_addc_u32 s41, s41, 0
	s_mov_b32 m0, s43
	v_lshl_add_u64 v[250:251], s[40:41], 0, v[194:195]
	ds_read_b128 v[174:177], v226 offset:32768
	ds_read_b128 v[178:181], v226 offset:33792
	ds_read_b128 v[182:185], v226 offset:34816
	ds_read_b128 v[186:189], v226 offset:35840
	ds_read_b128 v[190:193], v226 offset:36864
	ds_read_b128 v[238:241], v226 offset:37888
	ds_read_b128 v[242:245], v226 offset:38912
	ds_read_b128 v[246:249], v226 offset:39936
	global_load_lds_dwordx4 v[250:251], off
	v_lshl_add_u64 v[250:251], s[40:41], 0, v[204:205]
	s_mov_b32 m0, s44
	s_nop 0
	global_load_lds_dwordx4 v[250:251], off
	s_waitcnt vmcnt(8)
	s_waitcnt lgkmcnt(0)
	s_barrier
	s_waitcnt lgkmcnt(0)
	v_mfma_i32_16x16x64_i8 v[30:33], v[130:133], v[174:177], v[30:33]
	v_mfma_i32_16x16x64_i8 v[30:33], v[134:137], v[178:181], v[30:33]
	v_mfma_i32_16x16x64_i8 v[26:29], v[138:141], v[174:177], v[26:29]
	v_mfma_i32_16x16x64_i8 v[26:29], v[142:145], v[178:181], v[26:29]
	v_mfma_i32_16x16x64_i8 v[46:49], v[130:133], v[182:185], v[46:49]
	v_mfma_i32_16x16x64_i8 v[46:49], v[134:137], v[186:189], v[46:49]
	v_mfma_i32_16x16x64_i8 v[42:45], v[138:141], v[182:185], v[42:45]
	v_mfma_i32_16x16x64_i8 v[42:45], v[142:145], v[186:189], v[42:45]
	v_mfma_i32_16x16x64_i8 v[74:77], v[130:133], v[190:193], v[74:77]
	v_mfma_i32_16x16x64_i8 v[74:77], v[134:137], v[238:241], v[74:77]
	v_mfma_i32_16x16x64_i8 v[70:73], v[138:141], v[190:193], v[70:73]
	v_mfma_i32_16x16x64_i8 v[70:73], v[142:145], v[238:241], v[70:73]
	v_mfma_i32_16x16x64_i8 v[94:97], v[130:133], v[242:245], v[94:97]
	v_mfma_i32_16x16x64_i8 v[94:97], v[134:137], v[246:249], v[94:97]
	v_mfma_i32_16x16x64_i8 v[90:93], v[138:141], v[242:245], v[90:93]
	v_mfma_i32_16x16x64_i8 v[90:93], v[142:145], v[246:249], v[90:93]
	v_mfma_i32_16x16x64_i8 v[38:41], v[146:149], v[174:177], v[38:41]
	v_mfma_i32_16x16x64_i8 v[38:41], v[150:153], v[178:181], v[38:41]
	v_mfma_i32_16x16x64_i8 v[34:37], v[154:157], v[174:177], v[34:37]
	v_mfma_i32_16x16x64_i8 v[34:37], v[158:161], v[178:181], v[34:37]
	v_mfma_i32_16x16x64_i8 v[58:61], v[146:149], v[182:185], v[58:61]
	v_mfma_i32_16x16x64_i8 v[58:61], v[150:153], v[186:189], v[58:61]
	v_mfma_i32_16x16x64_i8 v[54:57], v[154:157], v[182:185], v[54:57]
	v_mfma_i32_16x16x64_i8 v[54:57], v[158:161], v[186:189], v[54:57]
	v_mfma_i32_16x16x64_i8 v[86:89], v[146:149], v[190:193], v[86:89]
	v_mfma_i32_16x16x64_i8 v[86:89], v[150:153], v[238:241], v[86:89]
	v_mfma_i32_16x16x64_i8 v[82:85], v[154:157], v[190:193], v[82:85]
	v_mfma_i32_16x16x64_i8 v[82:85], v[158:161], v[238:241], v[82:85]
	v_mfma_i32_16x16x64_i8 v[102:105], v[146:149], v[242:245], v[102:105]
	v_mfma_i32_16x16x64_i8 v[102:105], v[150:153], v[246:249], v[102:105]
	v_mfma_i32_16x16x64_i8 v[98:101], v[154:157], v[242:245], v[98:101]
	v_mfma_i32_16x16x64_i8 v[98:101], v[158:161], v[246:249], v[98:101]
	s_barrier
	s_mov_b32 m0, s72
	v_lshl_add_u64 v[166:167], v[166:167], 0, s[6:7]
	s_add_u32 s38, s38, 0x80080
	ds_read_b128 v[174:177], v226 offset:49152
	ds_read_b128 v[178:181], v226 offset:50176
	ds_read_b128 v[182:185], v226 offset:51200
	ds_read_b128 v[186:189], v226 offset:52224
	ds_read_b128 v[190:193], v226 offset:53248
	ds_read_b128 v[238:241], v226 offset:54272
	ds_read_b128 v[242:245], v226 offset:55296
	ds_read_b128 v[246:249], v226 offset:56320
	global_load_lds_dwordx4 v[166:167], off
	v_lshl_add_u64 v[166:167], v[168:169], 0, s[6:7]
	s_mov_b32 m0, s73
	s_addc_u32 s39, s39, 0
	global_load_lds_dwordx4 v[166:167], off
	v_lshl_add_u64 v[166:167], s[38:39], 0, v[202:203]
	s_mov_b32 m0, s74
	s_nop 0
	global_load_lds_dwordx4 v[166:167], off
	v_lshl_add_u64 v[166:167], s[38:39], 0, v[206:207]
	s_mov_b32 m0, s75
	s_nop 0
	global_load_lds_dwordx4 v[166:167], off
	v_lshl_add_u64 v[166:167], v[170:171], 0, s[6:7]
	s_mov_b32 m0, s51
	s_nop 0
	global_load_lds_dwordx4 v[166:167], off
	v_lshl_add_u64 v[166:167], v[172:173], 0, s[6:7]
	s_mov_b32 m0, s53
	s_nop 0
	global_load_lds_dwordx4 v[166:167], off
	s_waitcnt vmcnt(8)
	s_waitcnt lgkmcnt(0)
	s_barrier
	s_waitcnt lgkmcnt(0)
	v_mfma_i32_16x16x64_i8 v[110:113], v[130:133], v[174:177], v[110:113]
	v_mfma_i32_16x16x64_i8 v[110:113], v[134:137], v[178:181], v[110:113]
	v_mfma_i32_16x16x64_i8 v[106:109], v[138:141], v[174:177], v[106:109]
	v_mfma_i32_16x16x64_i8 v[106:109], v[142:145], v[178:181], v[106:109]
	v_mfma_i32_16x16x64_i8 v[126:129], v[130:133], v[182:185], v[126:129]
	v_mfma_i32_16x16x64_i8 v[126:129], v[134:137], v[186:189], v[126:129]
	v_mfma_i32_16x16x64_i8 v[118:121], v[138:141], v[182:185], v[118:121]
	v_mfma_i32_16x16x64_i8 v[118:121], v[142:145], v[186:189], v[118:121]
	v_mfma_i32_16x16x64_i8 v[62:65], v[130:133], v[190:193], v[62:65]
	v_mfma_i32_16x16x64_i8 v[62:65], v[134:137], v[238:241], v[62:65]
	v_mfma_i32_16x16x64_i8 v[50:53], v[138:141], v[190:193], v[50:53]
	v_mfma_i32_16x16x64_i8 v[50:53], v[142:145], v[238:241], v[50:53]
	v_mfma_i32_16x16x64_i8 v[14:17], v[130:133], v[242:245], v[14:17]
	v_mfma_i32_16x16x64_i8 v[14:17], v[134:137], v[246:249], v[14:17]
	v_mfma_i32_16x16x64_i8 v[10:13], v[138:141], v[242:245], v[10:13]
	v_mfma_i32_16x16x64_i8 v[10:13], v[142:145], v[246:249], v[10:13]
	v_mfma_i32_16x16x64_i8 v[122:125], v[146:149], v[174:177], v[122:125]
	v_mfma_i32_16x16x64_i8 v[122:125], v[150:153], v[178:181], v[122:125]
	v_mfma_i32_16x16x64_i8 v[114:117], v[154:157], v[174:177], v[114:117]
	v_mfma_i32_16x16x64_i8 v[114:117], v[158:161], v[178:181], v[114:117]
	v_mfma_i32_16x16x64_i8 v[78:81], v[146:149], v[182:185], v[78:81]
	v_mfma_i32_16x16x64_i8 v[78:81], v[150:153], v[186:189], v[78:81]
	v_mfma_i32_16x16x64_i8 v[66:69], v[154:157], v[182:185], v[66:69]
	v_mfma_i32_16x16x64_i8 v[66:69], v[158:161], v[186:189], v[66:69]
	v_mfma_i32_16x16x64_i8 v[22:25], v[146:149], v[190:193], v[22:25]
	v_mfma_i32_16x16x64_i8 v[22:25], v[150:153], v[238:241], v[22:25]
	v_mfma_i32_16x16x64_i8 v[18:21], v[154:157], v[190:193], v[18:21]
	v_mfma_i32_16x16x64_i8 v[18:21], v[158:161], v[238:241], v[18:21]
	v_mfma_i32_16x16x64_i8 v[6:9], v[146:149], v[242:245], v[6:9]
	v_mfma_i32_16x16x64_i8 v[6:9], v[150:153], v[246:249], v[6:9]
	v_mfma_i32_16x16x64_i8 v[2:5], v[154:157], v[242:245], v[2:5]
	v_mfma_i32_16x16x64_i8 v[2:5], v[158:161], v[246:249], v[2:5]
	s_barrier
	s_add_i32 s80, s80, 2
	s_add_u32 s36, s36, 0x100
	s_addc_u32 s37, s37, 0
	s_cmp_gt_u32 s80, 13
	s_cbranch_scc0 .LBB0_746
	s_nop 15
	s_nop 15
	s_and_b64 vcc, exec, s[8:9]
	s_cbranch_vccz .LBB0_749
	s_barrier

.LBB0_961:
	ds_read_b128 v[158:161], v185
	ds_read_b128 v[154:157], v185 offset:1024
	ds_read_b128 v[150:153], v185 offset:2048
	ds_read_b128 v[146:149], v185 offset:3072
	ds_read_b128 v[142:145], v186
	ds_read_b128 v[138:141], v186 offset:1024
	ds_read_b128 v[134:137], v186 offset:2048
	ds_read_b128 v[130:133], v186 offset:3072
	s_add_u32 s30, s28, 0xfff80080
	s_addc_u32 s31, s29, -1
	s_cmp_eq_u32 s45, 28
	s_cselect_b32 s35, s1, s31
	s_cselect_b32 s34, s15, s30
	s_cselect_b32 s31, s19, s44
	s_cselect_b32 s30, s42, s43
	v_lshl_add_u64 v[220:221], s[28:29], 0, v[170:171]
	s_add_i32 m0, s27, 0xc000
	ds_read_b128 v[174:177], v187
	ds_read_b128 v[178:181], v187 offset:1024
	ds_read_b128 v[188:191], v187 offset:2048
	ds_read_b128 v[192:195], v187 offset:3072
	ds_read_b128 v[202:205], v187 offset:4096
	ds_read_b128 v[206:209], v187 offset:5120
	ds_read_b128 v[210:213], v187 offset:6144
	ds_read_b128 v[214:217], v187 offset:7168
	global_load_lds_dwordx4 v[220:221], off
	v_lshl_add_u64 v[220:221], s[28:29], 0, v[172:173]
	s_add_i32 m0, s27, 0xe000
	s_nop 0
	global_load_lds_dwordx4 v[220:221], off
	s_waitcnt vmcnt(8)
	s_waitcnt lgkmcnt(0)
	s_barrier
	s_waitcnt lgkmcnt(0)
	v_mfma_i32_16x16x64_i8 v[126:129], v[158:161], v[174:177], v[126:129]
	v_mfma_i32_16x16x64_i8 v[126:129], v[154:157], v[178:181], v[126:129]
	v_mfma_i32_16x16x64_i8 v[122:125], v[150:153], v[174:177], v[122:125]
	v_mfma_i32_16x16x64_i8 v[122:125], v[146:149], v[178:181], v[122:125]
	v_mfma_i32_16x16x64_i8 v[110:113], v[158:161], v[188:191], v[110:113]
	v_mfma_i32_16x16x64_i8 v[110:113], v[154:157], v[192:195], v[110:113]
	v_mfma_i32_16x16x64_i8 v[106:109], v[150:153], v[188:191], v[106:109]
	v_mfma_i32_16x16x64_i8 v[106:109], v[146:149], v[192:195], v[106:109]
	v_mfma_i32_16x16x64_i8 v[94:97], v[158:161], v[202:205], v[94:97]
	v_mfma_i32_16x16x64_i8 v[94:97], v[154:157], v[206:209], v[94:97]
	v_mfma_i32_16x16x64_i8 v[90:93], v[150:153], v[202:205], v[90:93]
	v_mfma_i32_16x16x64_i8 v[90:93], v[146:149], v[206:209], v[90:93]
	v_mfma_i32_16x16x64_i8 v[78:81], v[158:161], v[210:213], v[78:81]
	v_mfma_i32_16x16x64_i8 v[78:81], v[154:157], v[214:217], v[78:81]
	v_mfma_i32_16x16x64_i8 v[74:77], v[150:153], v[210:213], v[74:77]
	v_mfma_i32_16x16x64_i8 v[74:77], v[146:149], v[214:217], v[74:77]
	v_mfma_i32_16x16x64_i8 v[118:121], v[142:145], v[174:177], v[118:121]
	v_mfma_i32_16x16x64_i8 v[118:121], v[138:141], v[178:181], v[118:121]
	v_mfma_i32_16x16x64_i8 v[114:117], v[134:137], v[174:177], v[114:117]
	v_mfma_i32_16x16x64_i8 v[114:117], v[130:133], v[178:181], v[114:117]
	v_mfma_i32_16x16x64_i8 v[102:105], v[142:145], v[188:191], v[102:105]
	v_mfma_i32_16x16x64_i8 v[102:105], v[138:141], v[192:195], v[102:105]
	v_mfma_i32_16x16x64_i8 v[98:101], v[134:137], v[188:191], v[98:101]
	v_mfma_i32_16x16x64_i8 v[98:101], v[130:133], v[192:195], v[98:101]
	v_mfma_i32_16x16x64_i8 v[86:89], v[142:145], v[202:205], v[86:89]
	v_mfma_i32_16x16x64_i8 v[86:89], v[138:141], v[206:209], v[86:89]
	v_mfma_i32_16x16x64_i8 v[82:85], v[134:137], v[202:205], v[82:85]
	v_mfma_i32_16x16x64_i8 v[82:85], v[130:133], v[206:209], v[82:85]
	v_mfma_i32_16x16x64_i8 v[70:73], v[142:145], v[210:213], v[70:73]
	v_mfma_i32_16x16x64_i8 v[70:73], v[138:141], v[214:217], v[70:73]
	v_mfma_i32_16x16x64_i8 v[66:69], v[134:137], v[210:213], v[66:69]
	v_mfma_i32_16x16x64_i8 v[66:69], v[130:133], v[214:217], v[66:69]
	s_barrier
	s_add_i32 s46, s17, s9
	v_lshl_add_u64 v[174:175], s[30:31], 0, v[166:167]
	s_mov_b32 m0, s46
	ds_read_b128 v[188:191], v187 offset:16384
	ds_read_b128 v[192:195], v187 offset:17408
	ds_read_b128 v[202:205], v187 offset:18432
	ds_read_b128 v[206:209], v187 offset:19456
	ds_read_b128 v[210:213], v187 offset:20480
	ds_read_b128 v[214:217], v187 offset:21504
	ds_read_b128 v[220:223], v187 offset:22528
	ds_read_b128 v[224:227], v187 offset:23552
	global_load_lds_dwordx4 v[174:175], off
	s_add_i32 m0, s46, 0x2000
	s_add_u32 s46, s30, 0x80000
	v_lshl_add_u64 v[176:177], s[30:31], 0, v[162:163]
	s_addc_u32 s47, s31, 0
	s_add_i32 s48, s55, s9
	global_load_lds_dwordx4 v[176:177], off
	v_lshl_add_u64 v[178:179], s[46:47], 0, v[166:167]
	s_mov_b32 m0, s48
	v_lshl_add_u64 v[180:181], s[34:35], 0, v[164:165]
	global_load_lds_dwordx4 v[178:179], off
	v_lshl_add_u64 v[178:179], s[46:47], 0, v[162:163]
	s_add_i32 m0, s48, 0x2000
	s_nop 0
	global_load_lds_dwordx4 v[178:179], off
	v_lshl_add_u64 v[178:179], s[34:35], 0, v[168:169]
	s_mov_b32 m0, s27
	s_nop 0
	global_load_lds_dwordx4 v[178:179], off
	s_mov_b32 m0, s33
	s_nop 0
	global_load_lds_dwordx4 v[180:181], off
	s_waitcnt vmcnt(8)
	s_waitcnt lgkmcnt(0)
	s_barrier
	s_waitcnt lgkmcnt(0)
	v_mfma_i32_16x16x64_i8 v[62:65], v[158:161], v[188:191], v[62:65]
	v_mfma_i32_16x16x64_i8 v[62:65], v[154:157], v[192:195], v[62:65]
	v_mfma_i32_16x16x64_i8 v[58:61], v[150:153], v[188:191], v[58:61]
	v_mfma_i32_16x16x64_i8 v[58:61], v[146:149], v[192:195], v[58:61]
	v_mfma_i32_16x16x64_i8 v[46:49], v[158:161], v[202:205], v[46:49]
	v_mfma_i32_16x16x64_i8 v[46:49], v[154:157], v[206:209], v[46:49]
	v_mfma_i32_16x16x64_i8 v[42:45], v[150:153], v[202:205], v[42:45]
	v_mfma_i32_16x16x64_i8 v[42:45], v[146:149], v[206:209], v[42:45]
	v_mfma_i32_16x16x64_i8 v[30:33], v[158:161], v[210:213], v[30:33]
	v_mfma_i32_16x16x64_i8 v[30:33], v[154:157], v[214:217], v[30:33]
	v_mfma_i32_16x16x64_i8 v[26:29], v[150:153], v[210:213], v[26:29]
	v_mfma_i32_16x16x64_i8 v[26:29], v[146:149], v[214:217], v[26:29]
	v_mfma_i32_16x16x64_i8 v[14:17], v[158:161], v[220:223], v[14:17]
	v_mfma_i32_16x16x64_i8 v[14:17], v[154:157], v[224:227], v[14:17]
	v_mfma_i32_16x16x64_i8 v[10:13], v[150:153], v[220:223], v[10:13]
	v_mfma_i32_16x16x64_i8 v[10:13], v[146:149], v[224:227], v[10:13]
	v_mfma_i32_16x16x64_i8 v[54:57], v[142:145], v[188:191], v[54:57]
	v_mfma_i32_16x16x64_i8 v[54:57], v[138:141], v[192:195], v[54:57]
	v_mfma_i32_16x16x64_i8 v[50:53], v[134:137], v[188:191], v[50:53]
	v_mfma_i32_16x16x64_i8 v[50:53], v[130:133], v[192:195], v[50:53]
	v_mfma_i32_16x16x64_i8 v[38:41], v[142:145], v[202:205], v[38:41]
	v_mfma_i32_16x16x64_i8 v[38:41], v[138:141], v[206:209], v[38:41]
	v_mfma_i32_16x16x64_i8 v[34:37], v[134:137], v[202:205], v[34:37]
	v_mfma_i32_16x16x64_i8 v[34:37], v[130:133], v[206:209], v[34:37]
	v_mfma_i32_16x16x64_i8 v[22:25], v[142:145], v[210:213], v[22:25]
	v_mfma_i32_16x16x64_i8 v[22:25], v[138:141], v[214:217], v[22:25]
	v_mfma_i32_16x16x64_i8 v[18:21], v[134:137], v[210:213], v[18:21]
	v_mfma_i32_16x16x64_i8 v[18:21], v[130:133], v[214:217], v[18:21]
	v_mfma_i32_16x16x64_i8 v[6:9], v[142:145], v[220:223], v[6:9]
	v_mfma_i32_16x16x64_i8 v[6:9], v[138:141], v[224:227], v[6:9]
	v_mfma_i32_16x16x64_i8 v[2:5], v[134:137], v[220:223], v[2:5]
	v_mfma_i32_16x16x64_i8 v[2:5], v[130:133], v[224:227], v[2:5]
	s_barrier
	v_add_u32_e32 v142, s56, v183
	v_add_u32_e32 v158, s57, v183
	ds_read_b128 v[130:133], v142
	ds_read_b128 v[134:137], v142 offset:1024
	ds_read_b128 v[138:141], v142 offset:2048
	ds_read_b128 v[142:145], v142 offset:3072
	ds_read_b128 v[146:149], v158
	ds_read_b128 v[150:153], v158 offset:1024
	ds_read_b128 v[154:157], v158 offset:2048
	ds_read_b128 v[158:161], v158 offset:3072
	s_add_u32 s34, s34, 0x80000
	s_addc_u32 s35, s35, 0
	s_mov_b32 m0, s36
	v_lshl_add_u64 v[232:233], s[34:35], 0, v[168:169]
	ds_read_b128 v[188:191], v187 offset:32768
	ds_read_b128 v[192:195], v187 offset:33792
	ds_read_b128 v[202:205], v187 offset:34816
	ds_read_b128 v[206:209], v187 offset:35840
	ds_read_b128 v[210:213], v187 offset:36864
	ds_read_b128 v[214:217], v187 offset:37888
	ds_read_b128 v[220:223], v187 offset:38912
	ds_read_b128 v[224:227], v187 offset:39936
	global_load_lds_dwordx4 v[232:233], off
	v_lshl_add_u64 v[232:233], s[34:35], 0, v[164:165]
	s_mov_b32 m0, s37
	s_nop 0
	global_load_lds_dwordx4 v[232:233], off
	s_waitcnt vmcnt(8)
	s_waitcnt lgkmcnt(0)
	s_barrier
	s_waitcnt lgkmcnt(0)
	v_mfma_i32_16x16x64_i8 v[126:129], v[130:133], v[188:191], v[126:129]
	v_mfma_i32_16x16x64_i8 v[126:129], v[134:137], v[192:195], v[126:129]
	v_mfma_i32_16x16x64_i8 v[122:125], v[138:141], v[188:191], v[122:125]
	v_mfma_i32_16x16x64_i8 v[122:125], v[142:145], v[192:195], v[122:125]
	v_mfma_i32_16x16x64_i8 v[110:113], v[130:133], v[202:205], v[110:113]
	v_mfma_i32_16x16x64_i8 v[110:113], v[134:137], v[206:209], v[110:113]
	v_mfma_i32_16x16x64_i8 v[106:109], v[138:141], v[202:205], v[106:109]
	v_mfma_i32_16x16x64_i8 v[106:109], v[142:145], v[206:209], v[106:109]
	v_mfma_i32_16x16x64_i8 v[94:97], v[130:133], v[210:213], v[94:97]
	v_mfma_i32_16x16x64_i8 v[94:97], v[134:137], v[214:217], v[94:97]
	v_mfma_i32_16x16x64_i8 v[90:93], v[138:141], v[210:213], v[90:93]
	v_mfma_i32_16x16x64_i8 v[90:93], v[142:145], v[214:217], v[90:93]
	v_mfma_i32_16x16x64_i8 v[78:81], v[130:133], v[220:223], v[78:81]
	v_mfma_i32_16x16x64_i8 v[78:81], v[134:137], v[224:227], v[78:81]
	v_mfma_i32_16x16x64_i8 v[74:77], v[138:141], v[220:223], v[74:77]
	v_mfma_i32_16x16x64_i8 v[74:77], v[142:145], v[224:227], v[74:77]
	v_mfma_i32_16x16x64_i8 v[118:121], v[146:149], v[188:191], v[118:121]
	v_mfma_i32_16x16x64_i8 v[118:121], v[150:153], v[192:195], v[118:121]
	v_mfma_i32_16x16x64_i8 v[114:117], v[154:157], v[188:191], v[114:117]
	v_mfma_i32_16x16x64_i8 v[114:117], v[158:161], v[192:195], v[114:117]
	v_mfma_i32_16x16x64_i8 v[102:105], v[146:149], v[202:205], v[102:105]
	v_mfma_i32_16x16x64_i8 v[102:105], v[150:153], v[206:209], v[102:105]
	v_mfma_i32_16x16x64_i8 v[98:101], v[154:157], v[202:205], v[98:101]
	v_mfma_i32_16x16x64_i8 v[98:101], v[158:161], v[206:209], v[98:101]
	v_mfma_i32_16x16x64_i8 v[86:89], v[146:149], v[210:213], v[86:89]
	v_mfma_i32_16x16x64_i8 v[86:89], v[150:153], v[214:217], v[86:89]
	v_mfma_i32_16x16x64_i8 v[82:85], v[154:157], v[210:213], v[82:85]
	v_mfma_i32_16x16x64_i8 v[82:85], v[158:161], v[214:217], v[82:85]
	v_mfma_i32_16x16x64_i8 v[70:73], v[146:149], v[220:223], v[70:73]
	v_mfma_i32_16x16x64_i8 v[70:73], v[150:153], v[224:227], v[70:73]
	v_mfma_i32_16x16x64_i8 v[66:69], v[154:157], v[220:223], v[66:69]
	v_mfma_i32_16x16x64_i8 v[66:69], v[158:161], v[224:227], v[66:69]
	s_barrier
	s_add_i32 s34, s56, s9
	v_lshl_add_u64 v[174:175], v[174:175], 0, s[4:5]
	s_mov_b32 m0, s34
	ds_read_b128 v[188:191], v187 offset:49152
	ds_read_b128 v[192:195], v187 offset:50176
	ds_read_b128 v[202:205], v187 offset:51200
	ds_read_b128 v[206:209], v187 offset:52224
	ds_read_b128 v[210:213], v187 offset:53248
	ds_read_b128 v[214:217], v187 offset:54272
	ds_read_b128 v[220:223], v187 offset:55296
	ds_read_b128 v[224:227], v187 offset:56320
	global_load_lds_dwordx4 v[174:175], off
	s_add_i32 m0, s34, 0x2000
	s_add_u32 s30, s30, 0x80080
	v_lshl_add_u64 v[174:175], v[176:177], 0, s[4:5]
	s_addc_u32 s31, s31, 0
	s_add_i32 s34, s57, s9
	global_load_lds_dwordx4 v[174:175], off
	v_lshl_add_u64 v[174:175], s[30:31], 0, v[166:167]
	s_mov_b32 m0, s34
	s_nop 0
	global_load_lds_dwordx4 v[174:175], off
	v_lshl_add_u64 v[174:175], s[30:31], 0, v[162:163]
	s_add_i32 m0, s34, 0x2000
	s_nop 0
	global_load_lds_dwordx4 v[174:175], off
	v_lshl_add_u64 v[174:175], v[178:179], 0, s[4:5]
	s_mov_b32 m0, s39
	s_nop 0
	global_load_lds_dwordx4 v[174:175], off
	v_lshl_add_u64 v[174:175], v[180:181], 0, s[4:5]
	s_mov_b32 m0, s40
	s_nop 0
	global_load_lds_dwordx4 v[174:175], off
	s_waitcnt vmcnt(8)
	s_waitcnt lgkmcnt(0)
	s_barrier
	s_waitcnt lgkmcnt(0)
	v_mfma_i32_16x16x64_i8 v[62:65], v[130:133], v[188:191], v[62:65]
	v_mfma_i32_16x16x64_i8 v[62:65], v[134:137], v[192:195], v[62:65]
	v_mfma_i32_16x16x64_i8 v[58:61], v[138:141], v[188:191], v[58:61]
	v_mfma_i32_16x16x64_i8 v[58:61], v[142:145], v[192:195], v[58:61]
	v_mfma_i32_16x16x64_i8 v[46:49], v[130:133], v[202:205], v[46:49]
	v_mfma_i32_16x16x64_i8 v[46:49], v[134:137], v[206:209], v[46:49]
	v_mfma_i32_16x16x64_i8 v[42:45], v[138:141], v[202:205], v[42:45]
	v_mfma_i32_16x16x64_i8 v[42:45], v[142:145], v[206:209], v[42:45]
	v_mfma_i32_16x16x64_i8 v[30:33], v[130:133], v[210:213], v[30:33]
	v_mfma_i32_16x16x64_i8 v[30:33], v[134:137], v[214:217], v[30:33]
	v_mfma_i32_16x16x64_i8 v[26:29], v[138:141], v[210:213], v[26:29]
	v_mfma_i32_16x16x64_i8 v[26:29], v[142:145], v[214:217], v[26:29]
	v_mfma_i32_16x16x64_i8 v[14:17], v[130:133], v[220:223], v[14:17]
	v_mfma_i32_16x16x64_i8 v[14:17], v[134:137], v[224:227], v[14:17]
	v_mfma_i32_16x16x64_i8 v[10:13], v[138:141], v[220:223], v[10:13]
	v_mfma_i32_16x16x64_i8 v[10:13], v[142:145], v[224:227], v[10:13]
	v_mfma_i32_16x16x64_i8 v[54:57], v[146:149], v[188:191], v[54:57]
	v_mfma_i32_16x16x64_i8 v[54:57], v[150:153], v[192:195], v[54:57]
	v_mfma_i32_16x16x64_i8 v[50:53], v[154:157], v[188:191], v[50:53]
	v_mfma_i32_16x16x64_i8 v[50:53], v[158:161], v[192:195], v[50:53]
	v_mfma_i32_16x16x64_i8 v[38:41], v[146:149], v[202:205], v[38:41]
	v_mfma_i32_16x16x64_i8 v[38:41], v[150:153], v[206:209], v[38:41]
	v_mfma_i32_16x16x64_i8 v[34:37], v[154:157], v[202:205], v[34:37]
	v_mfma_i32_16x16x64_i8 v[34:37], v[158:161], v[206:209], v[34:37]
	v_mfma_i32_16x16x64_i8 v[22:25], v[146:149], v[210:213], v[22:25]
	v_mfma_i32_16x16x64_i8 v[22:25], v[150:153], v[214:217], v[22:25]
	v_mfma_i32_16x16x64_i8 v[18:21], v[154:157], v[210:213], v[18:21]
	v_mfma_i32_16x16x64_i8 v[18:21], v[158:161], v[214:217], v[18:21]
	v_mfma_i32_16x16x64_i8 v[6:9], v[146:149], v[220:223], v[6:9]
	v_mfma_i32_16x16x64_i8 v[6:9], v[150:153], v[224:227], v[6:9]
	v_mfma_i32_16x16x64_i8 v[2:5], v[154:157], v[220:223], v[2:5]
	v_mfma_i32_16x16x64_i8 v[2:5], v[158:161], v[224:227], v[2:5]
	s_barrier
	s_add_i32 s45, s45, 2
	s_add_u32 s28, s28, 0x100
	s_addc_u32 s29, s29, 0
	s_add_u32 s43, s43, 0x100
	s_addc_u32 s44, s44, 0
	s_cmp_gt_u32 s45, 29
	s_cbranch_scc0 .LBB0_961
	s_nop 15
	s_nop 15
	s_and_b64 vcc, exec, s[6:7]
	s_cbranch_vccz .LBB0_964
	s_barrier
